# cross-attention output: 32 row-per-lane dwordx2 stores per unit widened to 16 dwordx4 stores via v_permlane32_swap pairs (strategy 7.3)
# speedup vs baseline: 1.0115x; 1.0070x over previous
; DI void xattn_unit(const bf16_t* __restrict__ Qg, const bf16_t* __restrict__ Kg, const bf16_t* __restrict__ Vg, bf16_t* __restrict__ Og, lds_t* shm) {
;     ...
;   unsigned soff[2];
; #pragma unroll
;   for (int i = 0; i < 2; ++i) { unsigned r, c; inv_off_a(tid + 512 * i, r, c); soff[i] = (r * (unsigned)LDKV + c * 8u) * 2u; }
;   constexpr unsigned tstep = 64u * LDKV * 2u;
;   auto issue_tile = [&](const bf16_t* src, int t, unsigned lds_base) __attribute__((always_inline)) {
;     const char* sb = (const char*)src + (size_t)t * tstep; lds_t* base = shm + lds_base + wid * 1024;
; #pragma unroll
;     for (int im = 0; im < 2; ++im) { glds16(sb + im * 256, soff[0], base + im * 16384); glds16(sb + im * 256, soff[1], base + im * 16384 + 8192); }
;   };
;   __syncthreads();
; #pragma unroll
;   for (int t = 0; t < 4; ++t) issue_tile(Kg, t, t * 32768);
;   issue_tile(Vg, 0, 131072);
;   const unsigned q4 = (lane & 15) >> 2, pp = lane & 3, blk = (lane >> 4) & 1;
;   const unsigned xk = (l31 >> 2) & 3, kbase = 2048u * (l31 >> 3) + 64u * (l31 & 7);
;   const unsigned ka0 = kbase + 16u * ((unsigned)h ^ xk), ka2 = kbase + 16u * ((2u + h) ^ xk);
;   const unsigned vrow = 64u * (4u * h + q4), cl = 2u * blk + (pp >> 1);
;   const unsigned va0 = vrow + 16u * (cl ^ (unsigned)h) + 8u * (pp & 1), va1 = vrow + 16u * (cl ^ ((unsigned)h ^ 2u)) + 8u * (pp & 1);
;   const unsigned qoff = ((unsigned)l31 * (unsigned)LDQ + 8u * h) * 2u;
;   f32x16 S[4][2];
; #pragma unroll
;   for (int t = 0; t < 4; ++t)
; #pragma unroll
;     for (int kb = 0; kb < 2; ++kb)
; #pragma unroll
;       for (int i = 0; i < 16; ++i) S[t][kb][i] = 0.f;
;   asm volatile("s_waitcnt vmcnt(0)" ::: "memory");
;   __syncthreads();
; DI void cross_attn_own_tiles(const Params& p, lds_t* shm) {
;     ...
;     int pm, pn; if (!g8::tile_coords(i * (int)gridDim.x + (int)blockIdx.x, T_TOK / 256, 4, pm, pn)) break;
;     const int b = pm >> 5, hd = pn; const size_t r0 = (size_t)pm * 256 + wid * 32;
;     xattn_unit(Q + r0 * DM + hd * 256, KV + (size_t)b * 256 * 2048 + hd * 256, KV + (size_t)b * 256 * 2048 + 1024 + hd * 256, O + r0 * DM + hd * 256, shm);
.LBB0_629:
	s_add_i32 s0, s29, s0
	s_ashr_i32 s1, s0, 31
	s_lshr_b32 s1, s1, 27
	s_add_i32 s1, s0, s1
	s_ashr_i32 s28, s1, 5
	s_and_b32 s1, s1, 0xffe0
	s_sub_i32 s0, s0, s1
	s_bfe_i32 s1, s0, 0x80000
	s_bfe_u32 s1, s1, 0x3000c
	s_add_i32 s1, s0, s1
	s_bfe_i32 s29, s1, 0x80000
	s_and_b32 s1, s1, 0xf8
	s_sub_i32 s0, s0, s1
	s_lshl_b32 s28, s28, 3
	s_sext_i32_i8 s0, s0
	s_add_i32 s0, s28, s0
	s_ashr_i32 s1, s0, 31
	s_ashr_i32 s28, s0, 5
	s_lshl_b64 s[0:1], s[0:1], 18
	s_add_u32 s0, s0, s4
	s_addc_u32 s1, s1, s5
	s_lshl_b64 s[0:1], s[0:1], 1
	s_sext_i32_i16 s29, s29
	s_add_u32 s36, s26, s0
	s_addc_u32 s37, s27, s1
	s_lshl_b32 s29, s29, 5
	s_and_b32 s30, s29, 0xffffff00
	s_ashr_i32 s31, s30, 31
	s_lshl_b64 s[30:31], s[30:31], 1
	s_add_u32 s38, s36, s30
	s_addc_u32 s39, s37, s31
	s_ashr_i32 s29, s28, 31
	s_lshl_b64 s[28:29], s[28:29], 20
	s_add_u32 s28, s50, s28
	s_addc_u32 s29, s51, s29
	s_add_u32 s36, s28, s30
	s_addc_u32 s37, s29, s31
	s_add_u32 s0, s44, s0
	s_addc_u32 s1, s45, s1
	s_add_u32 s30, s0, s30
	v_mov_b32_e32 v6, v212
	s_addc_u32 s31, s1, s31
	s_mov_b32 s1, 0xfffff8
	v_bfe_u32 v1, v6, 2, 3
	v_lshrrev_b32_e32 v2, 4, v6
	v_and_or_b32 v2, v2, s1, v1
	v_lshrrev_b32_e32 v8, 3, v6
	v_lshrrev_b32_e32 v3, 2, v2
	v_and_b32_e32 v0, 12, v8
	v_xor_b32_e32 v3, v3, v6
	v_lshlrev_b32_e32 v7, 4, v6
	v_and_or_b32 v3, v3, 3, v0
	v_lshlrev_b32_e32 v2, 12, v2
	v_lshl_or_b32 v160, v3, 4, v2
	v_add_u32_e32 v2, 0x2000, v7
	v_readfirstlane_b32 s0, v6
	v_lshrrev_b32_e32 v2, 8, v2
	v_and_or_b32 v1, v2, s1, v1
	s_lshl_b32 s0, s0, 4
	v_lshrrev_b32_e32 v2, 2, v1
	s_and_b32 s82, s0, 0xfffffc00
	v_xor_b32_e32 v2, v2, v6
	s_add_i32 s78, s82, 0
	v_and_or_b32 v0, v2, 3, v0
	v_lshlrev_b32_e32 v1, 12, v1
	s_mov_b32 m0, s78
	v_lshl_or_b32 v162, v0, 4, v1
	s_barrier
	v_lshl_add_u64 v[0:1], s[36:37], 0, v[160:161]
	global_load_lds_dwordx4 v160, s[36:37]
	s_add_i32 m0, s78, 0x2000
	s_mov_b64 s[0:1], 0x100
	global_load_lds_dwordx4 v162, s[36:37]
	s_add_i32 m0, s78, 0x4000
	v_lshl_add_u64 v[4:5], v[0:1], 0, s[0:1]
	v_mov_b32_e32 v163, v161
	global_load_lds_dwordx4 v[4:5], off
	s_add_i32 m0, s78, 0x6000
	v_lshl_add_u64 v[2:3], s[36:37], 0, v[162:163]
	s_add_u32 s28, s36, 0x40000
	v_lshl_add_u64 v[4:5], v[2:3], 0, s[0:1]
	s_addc_u32 s29, s37, 0
	s_add_i32 s67, s78, 0x8000
	global_load_lds_dwordx4 v[4:5], off
	s_mov_b32 m0, s67
	s_add_i32 s0, s78, 0xa000
	global_load_lds_dwordx4 v160, s[28:29]
	s_mov_b32 m0, s0
	v_bfe_u32 v163, v6, 5, 1
	global_load_lds_dwordx4 v162, s[28:29]
	s_add_u32 s28, s36, 0x40100
	s_addc_u32 s29, s37, 0
	s_add_i32 s1, s78, 0xc000
	s_add_i32 vcc_lo, s78, 0xe000
	s_mov_b32 m0, s1
	s_add_u32 s68, s36, 0x80000
	global_load_lds_dwordx4 v160, s[28:29]
	s_mov_b32 m0, vcc_lo
	s_addc_u32 s69, s37, 0
	s_add_i32 vcc_hi, s78, 0x10000
	global_load_lds_dwordx4 v162, s[28:29]
	s_mov_b32 m0, vcc_hi
	s_add_i32 s28, s78, 0x12000
	global_load_lds_dwordx4 v160, s[68:69]
	s_mov_b32 m0, s28
	s_add_u32 s76, s36, 0x80100
	global_load_lds_dwordx4 v162, s[68:69]
	s_addc_u32 s77, s37, 0
	s_add_i32 s29, s78, 0x14000
	s_add_i32 s68, s78, 0x16000
	s_mov_b32 m0, s29
	s_add_u32 s80, s36, 0xc0000
	global_load_lds_dwordx4 v160, s[76:77]
	s_mov_b32 m0, s68
	s_addc_u32 s81, s37, 0
	s_add_i32 s69, s78, 0x18000
	global_load_lds_dwordx4 v162, s[76:77]
	s_mov_b32 m0, s69
	s_add_i32 s76, s78, 0x1a000
	global_load_lds_dwordx4 v160, s[80:81]
	s_mov_b32 m0, s76
	v_and_b32_e32 v132, 0xc0, v7
	global_load_lds_dwordx4 v162, s[80:81]
	s_add_u32 s80, s36, 0xc0100
	s_addc_u32 s81, s37, 0
	s_add_i32 s77, s78, 0x1c000
	s_mov_b32 m0, s77
	s_add_i32 s78, s78, 0x1e000
	global_load_lds_dwordx4 v160, s[80:81]
	s_mov_b32 m0, s78
	s_add_i32 s79, s14, s82
	global_load_lds_dwordx4 v162, s[80:81]
	s_mov_b64 s[80:81], 0x800
	v_lshl_add_u64 v[4:5], v[0:1], 0, s[80:81]
	s_mov_b32 m0, s79
	v_or_b32_e32 v7, 2, v163
	global_load_lds_dwordx4 v[4:5], off
	s_add_i32 m0, s79, 0x2000
	v_lshl_add_u64 v[4:5], v[2:3], 0, s[80:81]
	s_mov_b64 s[80:81], 0x900
	global_load_lds_dwordx4 v[4:5], off
	s_add_i32 m0, s79, 0x4000
	v_lshl_add_u64 v[0:1], v[0:1], 0, s[80:81]
	global_load_lds_dwordx4 v[0:1], off
	s_add_i32 m0, s79, 0x6000
	v_lshl_add_u64 v[0:1], v[2:3], 0, s[80:81]
	global_load_lds_dwordx4 v[0:1], off
	v_lshlrev_b32_e32 v1, 6, v6
	v_and_b32_e32 v5, 0x1c0, v1
	v_and_b32_e32 v1, 2, v8
	v_bfe_u32 v2, v6, 1, 1
	v_bitop3_b32 v3, v1, v163, v2 bitop3:0x36
	v_bitop3_b32 v1, v1, v7, v2 bitop3:0x36
	s_waitcnt vmcnt(0)
	v_lshlrev_b32_e32 v165, 4, v1
	v_lshlrev_b32_e32 v1, 11, v6
	v_lshlrev_b32_e32 v0, 8, v6
	v_and_b32_e32 v164, 0xf800, v1
	v_lshrrev_b32_e32 v4, 5, v6
	v_lshlrev_b32_e32 v169, 3, v6
	v_bfe_u32 v130, v6, 2, 2
	v_and_b32_e32 v6, 0x1800, v0
	v_lshlrev_b32_e32 v166, 4, v3
	v_lshl_or_b32 v128, v163, 4, v164
	s_waitcnt vmcnt(0) lgkmcnt(0)
	s_barrier
; #define LDSP(T, p) ((__attribute__((address_space(3))) T*)(p))
; #define MFMA32(a, b, c) __builtin_amdgcn_mfma_f32_32x32x16_bf16((a), (b), (c), 0, 0, 0)
; DI void xattn_unit(const bf16_t* __restrict__ Qg, const bf16_t* __restrict__ Kg, const bf16_t* __restrict__ Vg, bf16_t* __restrict__ Og, lds_t* shm) {
;     ...
; #pragma unroll
;   for (int ss = 0; ss < 16; ++ss) {
;     const int cgl = 2 * ss, img = cgl >> 4;
;     const bf16x8 qv = gld<bf16x8>(Qg + 16 * ss, qoff);
; #pragma unroll
;     for (int t = 0; t < 4; ++t)
; #pragma unroll
;       for (int kb = 0; kb < 2; ++kb) {
;         const bf16x8 kf = *LDSP(const bf16x8, shm + t * 32768 + img * 16384 + kb * 8192 + 512 * ((cgl & 15) >> 2) + ((cgl & 2) ? ka2 : ka0));
;         S[t][kb] = MFMA32(kf, qv, S[t][kb]);
;       }
;   }
	global_load_dwordx4 v[172:175], v128, s[38:39]
	global_load_dwordx4 v[176:179], v128, s[38:39] offset:32
	global_load_dwordx4 v[180:183], v128, s[38:39] offset:64
	global_load_dwordx4 v[184:187], v128, s[38:39] offset:96
	global_load_dwordx4 v[188:191], v128, s[38:39] offset:128
	global_load_dwordx4 v[192:195], v128, s[38:39] offset:160
	global_load_dwordx4 v[196:199], v128, s[38:39] offset:192
	global_load_dwordx4 v[200:203], v128, s[38:39] offset:224
	global_load_dwordx4 v[204:207], v128, s[38:39] offset:256
	global_load_dwordx4 v[208:211], v128, s[38:39] offset:288
	global_load_dwordx4 v[216:219], v128, s[38:39] offset:320
	global_load_dwordx4 v[220:223], v128, s[38:39] offset:352
	global_load_dwordx4 v[224:227], v128, s[38:39] offset:384
	global_load_dwordx4 v[228:231], v128, s[38:39] offset:416
	global_load_dwordx4 v[232:235], v128, s[38:39] offset:448
	global_load_dwordx4 v[236:239], v128, s[38:39] offset:480
	v_bitop3_b32 v4, v4, v130, 1 bitop3:0x6c
	v_add3_u32 v131, 0, v6, v5
	v_lshl_add_u32 v129, v4, 4, v131
	v_bitop3_b32 v130, v163, v130, 2 bitop3:0x36
	v_lshl_add_u32 v133, v130, 4, v131
	v_lshl_or_b32 v170, v163, 8, v132
	v_add_u32_e32 v248, 0x10000, v129
	v_add_u32_e32 v249, 0x10000, v133
	ds_read_b128 v[144:147], v129
	ds_read_b128 v[148:151], v129 offset:8192
	ds_read_b128 v[152:155], v129 offset:32768
	ds_read_b128 v[156:159], v129 offset:40960
	s_waitcnt vmcnt(15) lgkmcnt(3)
	v_mfma_f32_32x32x16_bf16 v[112:127], v[144:147], v[172:175], 0
	ds_read_b128 v[144:147], v248
	s_waitcnt lgkmcnt(3)
	v_mfma_f32_32x32x16_bf16 v[96:111], v[148:151], v[172:175], 0
	ds_read_b128 v[148:151], v248 offset:8192
	s_waitcnt lgkmcnt(3)
	v_mfma_f32_32x32x16_bf16 v[80:95], v[152:155], v[172:175], 0
	ds_read_b128 v[152:155], v248 offset:32768
	s_waitcnt lgkmcnt(3)
	v_mfma_f32_32x32x16_bf16 v[64:79], v[156:159], v[172:175], 0
	ds_read_b128 v[156:159], v248 offset:40960
	s_waitcnt lgkmcnt(3)
	v_mfma_f32_32x32x16_bf16 v[48:63], v[144:147], v[172:175], 0
	ds_read_b128 v[144:147], v133
	s_waitcnt lgkmcnt(3)
	v_mfma_f32_32x32x16_bf16 v[32:47], v[148:151], v[172:175], 0
	ds_read_b128 v[148:151], v133 offset:8192
	s_waitcnt lgkmcnt(3)
	v_mfma_f32_32x32x16_bf16 v[16:31], v[152:155], v[172:175], 0
	ds_read_b128 v[152:155], v133 offset:32768
	s_waitcnt lgkmcnt(3)
	v_mfma_f32_32x32x16_bf16 v[0:15], v[156:159], v[172:175], 0
	ds_read_b128 v[156:159], v133 offset:40960
	s_waitcnt vmcnt(14) lgkmcnt(3)
	v_mfma_f32_32x32x16_bf16 v[112:127], v[144:147], v[176:179], v[112:127]
	ds_read_b128 v[144:147], v249
	s_waitcnt lgkmcnt(3)
	v_mfma_f32_32x32x16_bf16 v[96:111], v[148:151], v[176:179], v[96:111]
	ds_read_b128 v[148:151], v249 offset:8192
	s_waitcnt lgkmcnt(3)
	v_mfma_f32_32x32x16_bf16 v[80:95], v[152:155], v[176:179], v[80:95]
	ds_read_b128 v[152:155], v249 offset:32768
	s_waitcnt lgkmcnt(3)
	v_mfma_f32_32x32x16_bf16 v[64:79], v[156:159], v[176:179], v[64:79]
	ds_read_b128 v[156:159], v249 offset:40960
	s_waitcnt lgkmcnt(3)
	v_mfma_f32_32x32x16_bf16 v[48:63], v[144:147], v[176:179], v[48:63]
	ds_read_b128 v[144:147], v129 offset:512
	s_waitcnt lgkmcnt(3)
	v_mfma_f32_32x32x16_bf16 v[32:47], v[148:151], v[176:179], v[32:47]
	ds_read_b128 v[148:151], v129 offset:8704
	s_waitcnt lgkmcnt(3)
	v_mfma_f32_32x32x16_bf16 v[16:31], v[152:155], v[176:179], v[16:31]
	ds_read_b128 v[152:155], v129 offset:33280
	s_waitcnt lgkmcnt(3)
	v_mfma_f32_32x32x16_bf16 v[0:15], v[156:159], v[176:179], v[0:15]
	ds_read_b128 v[156:159], v129 offset:41472
	s_waitcnt vmcnt(13) lgkmcnt(3)
	v_mfma_f32_32x32x16_bf16 v[112:127], v[144:147], v[180:183], v[112:127]
	ds_read_b128 v[144:147], v248 offset:512
	s_waitcnt lgkmcnt(3)
	v_mfma_f32_32x32x16_bf16 v[96:111], v[148:151], v[180:183], v[96:111]
	ds_read_b128 v[148:151], v248 offset:8704
	s_waitcnt lgkmcnt(3)
	v_mfma_f32_32x32x16_bf16 v[80:95], v[152:155], v[180:183], v[80:95]
	ds_read_b128 v[152:155], v248 offset:33280
	s_waitcnt lgkmcnt(3)
	v_mfma_f32_32x32x16_bf16 v[64:79], v[156:159], v[180:183], v[64:79]
	ds_read_b128 v[156:159], v248 offset:41472
	s_waitcnt lgkmcnt(3)
	v_mfma_f32_32x32x16_bf16 v[48:63], v[144:147], v[180:183], v[48:63]
	ds_read_b128 v[144:147], v133 offset:512
	s_waitcnt lgkmcnt(3)
	v_mfma_f32_32x32x16_bf16 v[32:47], v[148:151], v[180:183], v[32:47]
	ds_read_b128 v[148:151], v133 offset:8704
	s_waitcnt lgkmcnt(3)
	v_mfma_f32_32x32x16_bf16 v[16:31], v[152:155], v[180:183], v[16:31]
	ds_read_b128 v[152:155], v133 offset:33280
	s_waitcnt lgkmcnt(3)
	v_mfma_f32_32x32x16_bf16 v[0:15], v[156:159], v[180:183], v[0:15]
	ds_read_b128 v[156:159], v133 offset:41472
	s_waitcnt vmcnt(12) lgkmcnt(3)
	v_mfma_f32_32x32x16_bf16 v[112:127], v[144:147], v[184:187], v[112:127]
	ds_read_b128 v[144:147], v249 offset:512
	s_waitcnt lgkmcnt(3)
	v_mfma_f32_32x32x16_bf16 v[96:111], v[148:151], v[184:187], v[96:111]
	ds_read_b128 v[148:151], v249 offset:8704
	s_waitcnt lgkmcnt(3)
	v_mfma_f32_32x32x16_bf16 v[80:95], v[152:155], v[184:187], v[80:95]
	ds_read_b128 v[152:155], v249 offset:33280
	s_waitcnt lgkmcnt(3)
	v_mfma_f32_32x32x16_bf16 v[64:79], v[156:159], v[184:187], v[64:79]
	ds_read_b128 v[156:159], v249 offset:41472
	s_waitcnt lgkmcnt(3)
	v_mfma_f32_32x32x16_bf16 v[48:63], v[144:147], v[184:187], v[48:63]
	ds_read_b128 v[144:147], v129 offset:1024
	s_waitcnt lgkmcnt(3)
	v_mfma_f32_32x32x16_bf16 v[32:47], v[148:151], v[184:187], v[32:47]
	ds_read_b128 v[148:151], v129 offset:9216
	s_waitcnt lgkmcnt(3)
	v_mfma_f32_32x32x16_bf16 v[16:31], v[152:155], v[184:187], v[16:31]
	ds_read_b128 v[152:155], v129 offset:33792
	s_waitcnt lgkmcnt(3)
	v_mfma_f32_32x32x16_bf16 v[0:15], v[156:159], v[184:187], v[0:15]
	ds_read_b128 v[156:159], v129 offset:41984
	s_waitcnt vmcnt(11) lgkmcnt(3)
; #define LDSP(T, p) ((__attribute__((address_space(3))) T*)(p))
; #define MFMA32(a, b, c) __builtin_amdgcn_mfma_f32_32x32x16_bf16((a), (b), (c), 0, 0, 0)
; DI void xattn_unit(const bf16_t* __restrict__ Qg, const bf16_t* __restrict__ Kg, const bf16_t* __restrict__ Vg, bf16_t* __restrict__ Og, lds_t* shm) {
;     ...
; #pragma unroll
;   for (int ss = 0; ss < 16; ++ss) {
;     const int cgl = 2 * ss, img = cgl >> 4;
;     const bf16x8 qv = gld<bf16x8>(Qg + 16 * ss, qoff);
; #pragma unroll
;     for (int t = 0; t < 4; ++t)
; #pragma unroll
;       for (int kb = 0; kb < 2; ++kb) {
;         const bf16x8 kf = *LDSP(const bf16x8, shm + t * 32768 + img * 16384 + kb * 8192 + 512 * ((cgl & 15) >> 2) + ((cgl & 2) ? ka2 : ka0));
;         S[t][kb] = MFMA32(kf, qv, S[t][kb]);
;       }
;   }
	v_mfma_f32_32x32x16_bf16 v[112:127], v[144:147], v[188:191], v[112:127]
	ds_read_b128 v[144:147], v248 offset:1024
	s_waitcnt lgkmcnt(3)
	v_mfma_f32_32x32x16_bf16 v[96:111], v[148:151], v[188:191], v[96:111]
	ds_read_b128 v[148:151], v248 offset:9216
	s_waitcnt lgkmcnt(3)
	v_mfma_f32_32x32x16_bf16 v[80:95], v[152:155], v[188:191], v[80:95]
	ds_read_b128 v[152:155], v248 offset:33792
	s_waitcnt lgkmcnt(3)
	v_mfma_f32_32x32x16_bf16 v[64:79], v[156:159], v[188:191], v[64:79]
	ds_read_b128 v[156:159], v248 offset:41984
	s_waitcnt lgkmcnt(3)
	v_mfma_f32_32x32x16_bf16 v[48:63], v[144:147], v[188:191], v[48:63]
	ds_read_b128 v[144:147], v133 offset:1024
	s_waitcnt lgkmcnt(3)
	v_mfma_f32_32x32x16_bf16 v[32:47], v[148:151], v[188:191], v[32:47]
	ds_read_b128 v[148:151], v133 offset:9216
	s_waitcnt lgkmcnt(3)
	v_mfma_f32_32x32x16_bf16 v[16:31], v[152:155], v[188:191], v[16:31]
	ds_read_b128 v[152:155], v133 offset:33792
	s_waitcnt lgkmcnt(3)
	v_mfma_f32_32x32x16_bf16 v[0:15], v[156:159], v[188:191], v[0:15]
	ds_read_b128 v[156:159], v133 offset:41984
	s_waitcnt vmcnt(10) lgkmcnt(3)
	v_mfma_f32_32x32x16_bf16 v[112:127], v[144:147], v[192:195], v[112:127]
	ds_read_b128 v[144:147], v249 offset:1024
	s_waitcnt lgkmcnt(3)
	v_mfma_f32_32x32x16_bf16 v[96:111], v[148:151], v[192:195], v[96:111]
	ds_read_b128 v[148:151], v249 offset:9216
	s_waitcnt lgkmcnt(3)
	v_mfma_f32_32x32x16_bf16 v[80:95], v[152:155], v[192:195], v[80:95]
	ds_read_b128 v[152:155], v249 offset:33792
	s_waitcnt lgkmcnt(3)
	v_mfma_f32_32x32x16_bf16 v[64:79], v[156:159], v[192:195], v[64:79]
	ds_read_b128 v[156:159], v249 offset:41984
	s_waitcnt lgkmcnt(3)
	v_mfma_f32_32x32x16_bf16 v[48:63], v[144:147], v[192:195], v[48:63]
	ds_read_b128 v[144:147], v129 offset:1536
	s_waitcnt lgkmcnt(3)
	v_mfma_f32_32x32x16_bf16 v[32:47], v[148:151], v[192:195], v[32:47]
	ds_read_b128 v[148:151], v129 offset:9728
	s_waitcnt lgkmcnt(3)
	v_mfma_f32_32x32x16_bf16 v[16:31], v[152:155], v[192:195], v[16:31]
	ds_read_b128 v[152:155], v129 offset:34304
	s_waitcnt lgkmcnt(3)
	v_mfma_f32_32x32x16_bf16 v[0:15], v[156:159], v[192:195], v[0:15]
	ds_read_b128 v[156:159], v129 offset:42496
	s_waitcnt vmcnt(9) lgkmcnt(3)
	v_mfma_f32_32x32x16_bf16 v[112:127], v[144:147], v[196:199], v[112:127]
	ds_read_b128 v[144:147], v248 offset:1536
	s_waitcnt lgkmcnt(3)
	v_mfma_f32_32x32x16_bf16 v[96:111], v[148:151], v[196:199], v[96:111]
	ds_read_b128 v[148:151], v248 offset:9728
	s_waitcnt lgkmcnt(3)
	v_mfma_f32_32x32x16_bf16 v[80:95], v[152:155], v[196:199], v[80:95]
	ds_read_b128 v[152:155], v248 offset:34304
	s_waitcnt lgkmcnt(3)
	v_mfma_f32_32x32x16_bf16 v[64:79], v[156:159], v[196:199], v[64:79]
	ds_read_b128 v[156:159], v248 offset:42496
	s_waitcnt lgkmcnt(3)
	v_mfma_f32_32x32x16_bf16 v[48:63], v[144:147], v[196:199], v[48:63]
	ds_read_b128 v[144:147], v133 offset:1536
	s_waitcnt lgkmcnt(3)
	v_mfma_f32_32x32x16_bf16 v[32:47], v[148:151], v[196:199], v[32:47]
	ds_read_b128 v[148:151], v133 offset:9728
	s_waitcnt lgkmcnt(3)
	v_mfma_f32_32x32x16_bf16 v[16:31], v[152:155], v[196:199], v[16:31]
	ds_read_b128 v[152:155], v133 offset:34304
	s_waitcnt lgkmcnt(3)
	v_mfma_f32_32x32x16_bf16 v[0:15], v[156:159], v[196:199], v[0:15]
	ds_read_b128 v[156:159], v133 offset:42496
	s_waitcnt vmcnt(8) lgkmcnt(3)
	v_mfma_f32_32x32x16_bf16 v[112:127], v[144:147], v[200:203], v[112:127]
	ds_read_b128 v[144:147], v249 offset:1536
	s_waitcnt lgkmcnt(3)
	v_mfma_f32_32x32x16_bf16 v[96:111], v[148:151], v[200:203], v[96:111]
	ds_read_b128 v[148:151], v249 offset:9728
	s_waitcnt lgkmcnt(3)
	v_mfma_f32_32x32x16_bf16 v[80:95], v[152:155], v[200:203], v[80:95]
	ds_read_b128 v[152:155], v249 offset:34304
	s_waitcnt lgkmcnt(3)
	v_mfma_f32_32x32x16_bf16 v[64:79], v[156:159], v[200:203], v[64:79]
	ds_read_b128 v[156:159], v249 offset:42496
	s_waitcnt lgkmcnt(3)
	v_mfma_f32_32x32x16_bf16 v[48:63], v[144:147], v[200:203], v[48:63]
	ds_read_b128 v[144:147], v129 offset:16384
	s_waitcnt lgkmcnt(3)
	v_mfma_f32_32x32x16_bf16 v[32:47], v[148:151], v[200:203], v[32:47]
	ds_read_b128 v[148:151], v129 offset:24576
	s_waitcnt lgkmcnt(3)
	v_mfma_f32_32x32x16_bf16 v[16:31], v[152:155], v[200:203], v[16:31]
	ds_read_b128 v[152:155], v129 offset:49152
	s_waitcnt lgkmcnt(3)
	v_mfma_f32_32x32x16_bf16 v[0:15], v[156:159], v[200:203], v[0:15]
	ds_read_b128 v[156:159], v129 offset:57344
	s_waitcnt vmcnt(7) lgkmcnt(3)
	v_mfma_f32_32x32x16_bf16 v[112:127], v[144:147], v[204:207], v[112:127]
	ds_read_b128 v[144:147], v248 offset:16384
	s_waitcnt lgkmcnt(3)
	v_mfma_f32_32x32x16_bf16 v[96:111], v[148:151], v[204:207], v[96:111]
	ds_read_b128 v[148:151], v248 offset:24576
	s_waitcnt lgkmcnt(3)
	v_mfma_f32_32x32x16_bf16 v[80:95], v[152:155], v[204:207], v[80:95]
	ds_read_b128 v[152:155], v248 offset:49152
	s_waitcnt lgkmcnt(3)
	v_mfma_f32_32x32x16_bf16 v[64:79], v[156:159], v[204:207], v[64:79]
	ds_read_b128 v[156:159], v248 offset:57344
	s_waitcnt lgkmcnt(3)
	v_mfma_f32_32x32x16_bf16 v[48:63], v[144:147], v[204:207], v[48:63]
	ds_read_b128 v[144:147], v133 offset:16384
	s_waitcnt lgkmcnt(3)
	v_mfma_f32_32x32x16_bf16 v[32:47], v[148:151], v[204:207], v[32:47]
	ds_read_b128 v[148:151], v133 offset:24576
	s_waitcnt lgkmcnt(3)
	v_mfma_f32_32x32x16_bf16 v[16:31], v[152:155], v[204:207], v[16:31]
	ds_read_b128 v[152:155], v133 offset:49152
	s_waitcnt lgkmcnt(3)
	v_mfma_f32_32x32x16_bf16 v[0:15], v[156:159], v[204:207], v[0:15]
	ds_read_b128 v[156:159], v133 offset:57344
	s_waitcnt vmcnt(6) lgkmcnt(3)
	v_mfma_f32_32x32x16_bf16 v[112:127], v[144:147], v[208:211], v[112:127]
	ds_read_b128 v[144:147], v249 offset:16384
	s_waitcnt lgkmcnt(3)
; #define LDSP(T, p) ((__attribute__((address_space(3))) T*)(p))
; #define MFMA32(a, b, c) __builtin_amdgcn_mfma_f32_32x32x16_bf16((a), (b), (c), 0, 0, 0)
; DI void xattn_unit(const bf16_t* __restrict__ Qg, const bf16_t* __restrict__ Kg, const bf16_t* __restrict__ Vg, bf16_t* __restrict__ Og, lds_t* shm) {
;     ...
; #pragma unroll
;   for (int ss = 0; ss < 16; ++ss) {
;     const int cgl = 2 * ss, img = cgl >> 4;
;     const bf16x8 qv = gld<bf16x8>(Qg + 16 * ss, qoff);
; #pragma unroll
;     for (int t = 0; t < 4; ++t)
; #pragma unroll
;       for (int kb = 0; kb < 2; ++kb) {
;         const bf16x8 kf = *LDSP(const bf16x8, shm + t * 32768 + img * 16384 + kb * 8192 + 512 * ((cgl & 15) >> 2) + ((cgl & 2) ? ka2 : ka0));
;         S[t][kb] = MFMA32(kf, qv, S[t][kb]);
;       }
;   }
	v_mfma_f32_32x32x16_bf16 v[96:111], v[148:151], v[208:211], v[96:111]
	ds_read_b128 v[148:151], v249 offset:24576
	s_waitcnt lgkmcnt(3)
	v_mfma_f32_32x32x16_bf16 v[80:95], v[152:155], v[208:211], v[80:95]
	ds_read_b128 v[152:155], v249 offset:49152
	s_waitcnt lgkmcnt(3)
	v_mfma_f32_32x32x16_bf16 v[64:79], v[156:159], v[208:211], v[64:79]
	ds_read_b128 v[156:159], v249 offset:57344
	s_waitcnt lgkmcnt(3)
	v_mfma_f32_32x32x16_bf16 v[48:63], v[144:147], v[208:211], v[48:63]
	ds_read_b128 v[144:147], v129 offset:16896
	s_waitcnt lgkmcnt(3)
	v_mfma_f32_32x32x16_bf16 v[32:47], v[148:151], v[208:211], v[32:47]
	ds_read_b128 v[148:151], v129 offset:25088
	s_waitcnt lgkmcnt(3)
	v_mfma_f32_32x32x16_bf16 v[16:31], v[152:155], v[208:211], v[16:31]
	ds_read_b128 v[152:155], v129 offset:49664
	s_waitcnt lgkmcnt(3)
	v_mfma_f32_32x32x16_bf16 v[0:15], v[156:159], v[208:211], v[0:15]
	ds_read_b128 v[156:159], v129 offset:57856
	s_waitcnt vmcnt(5) lgkmcnt(3)
	v_mfma_f32_32x32x16_bf16 v[112:127], v[144:147], v[216:219], v[112:127]
	ds_read_b128 v[144:147], v248 offset:16896
	s_waitcnt lgkmcnt(3)
	v_mfma_f32_32x32x16_bf16 v[96:111], v[148:151], v[216:219], v[96:111]
	ds_read_b128 v[148:151], v248 offset:25088
	s_waitcnt lgkmcnt(3)
	v_mfma_f32_32x32x16_bf16 v[80:95], v[152:155], v[216:219], v[80:95]
	ds_read_b128 v[152:155], v248 offset:49664
	s_waitcnt lgkmcnt(3)
	v_mfma_f32_32x32x16_bf16 v[64:79], v[156:159], v[216:219], v[64:79]
	ds_read_b128 v[156:159], v248 offset:57856
	s_waitcnt lgkmcnt(3)
	v_mfma_f32_32x32x16_bf16 v[48:63], v[144:147], v[216:219], v[48:63]
	ds_read_b128 v[144:147], v133 offset:16896
	s_waitcnt lgkmcnt(3)
	v_mfma_f32_32x32x16_bf16 v[32:47], v[148:151], v[216:219], v[32:47]
	ds_read_b128 v[148:151], v133 offset:25088
	s_waitcnt lgkmcnt(3)
	v_mfma_f32_32x32x16_bf16 v[16:31], v[152:155], v[216:219], v[16:31]
	ds_read_b128 v[152:155], v133 offset:49664
	s_waitcnt lgkmcnt(3)
	v_mfma_f32_32x32x16_bf16 v[0:15], v[156:159], v[216:219], v[0:15]
	ds_read_b128 v[156:159], v133 offset:57856
	s_waitcnt vmcnt(4) lgkmcnt(3)
	v_mfma_f32_32x32x16_bf16 v[112:127], v[144:147], v[220:223], v[112:127]
	ds_read_b128 v[144:147], v249 offset:16896
	s_waitcnt lgkmcnt(3)
	v_mfma_f32_32x32x16_bf16 v[96:111], v[148:151], v[220:223], v[96:111]
	ds_read_b128 v[148:151], v249 offset:25088
	s_waitcnt lgkmcnt(3)
	v_mfma_f32_32x32x16_bf16 v[80:95], v[152:155], v[220:223], v[80:95]
	ds_read_b128 v[152:155], v249 offset:49664
	s_waitcnt lgkmcnt(3)
	v_mfma_f32_32x32x16_bf16 v[64:79], v[156:159], v[220:223], v[64:79]
	ds_read_b128 v[156:159], v249 offset:57856
	s_waitcnt lgkmcnt(3)
	v_mfma_f32_32x32x16_bf16 v[48:63], v[144:147], v[220:223], v[48:63]
	ds_read_b128 v[144:147], v129 offset:17408
	s_waitcnt lgkmcnt(3)
	v_mfma_f32_32x32x16_bf16 v[32:47], v[148:151], v[220:223], v[32:47]
	ds_read_b128 v[148:151], v129 offset:25600
	s_waitcnt lgkmcnt(3)
	v_mfma_f32_32x32x16_bf16 v[16:31], v[152:155], v[220:223], v[16:31]
	ds_read_b128 v[152:155], v129 offset:50176
	s_waitcnt lgkmcnt(3)
	v_mfma_f32_32x32x16_bf16 v[0:15], v[156:159], v[220:223], v[0:15]
	ds_read_b128 v[156:159], v129 offset:58368
	s_waitcnt vmcnt(3) lgkmcnt(3)
	v_mfma_f32_32x32x16_bf16 v[112:127], v[144:147], v[224:227], v[112:127]
	ds_read_b128 v[144:147], v248 offset:17408
	s_waitcnt lgkmcnt(3)
	v_mfma_f32_32x32x16_bf16 v[96:111], v[148:151], v[224:227], v[96:111]
	ds_read_b128 v[148:151], v248 offset:25600
	s_waitcnt lgkmcnt(3)
	v_mfma_f32_32x32x16_bf16 v[80:95], v[152:155], v[224:227], v[80:95]
	ds_read_b128 v[152:155], v248 offset:50176
	s_waitcnt lgkmcnt(3)
	v_mfma_f32_32x32x16_bf16 v[64:79], v[156:159], v[224:227], v[64:79]
	ds_read_b128 v[156:159], v248 offset:58368
	s_waitcnt lgkmcnt(3)
	v_mfma_f32_32x32x16_bf16 v[48:63], v[144:147], v[224:227], v[48:63]
	ds_read_b128 v[144:147], v133 offset:17408
	s_waitcnt lgkmcnt(3)
	v_mfma_f32_32x32x16_bf16 v[32:47], v[148:151], v[224:227], v[32:47]
	ds_read_b128 v[148:151], v133 offset:25600
	s_waitcnt lgkmcnt(3)
	v_mfma_f32_32x32x16_bf16 v[16:31], v[152:155], v[224:227], v[16:31]
	ds_read_b128 v[152:155], v133 offset:50176
	s_waitcnt lgkmcnt(3)
	v_mfma_f32_32x32x16_bf16 v[0:15], v[156:159], v[224:227], v[0:15]
	ds_read_b128 v[156:159], v133 offset:58368
	s_waitcnt vmcnt(2) lgkmcnt(3)
	v_mfma_f32_32x32x16_bf16 v[112:127], v[144:147], v[228:231], v[112:127]
	ds_read_b128 v[144:147], v249 offset:17408
	s_waitcnt lgkmcnt(3)
	v_mfma_f32_32x32x16_bf16 v[96:111], v[148:151], v[228:231], v[96:111]
	ds_read_b128 v[148:151], v249 offset:25600
	s_waitcnt lgkmcnt(3)
	v_mfma_f32_32x32x16_bf16 v[80:95], v[152:155], v[228:231], v[80:95]
	ds_read_b128 v[152:155], v249 offset:50176
	s_waitcnt lgkmcnt(3)
	v_mfma_f32_32x32x16_bf16 v[64:79], v[156:159], v[228:231], v[64:79]
	ds_read_b128 v[156:159], v249 offset:58368
	s_waitcnt lgkmcnt(3)
	v_mfma_f32_32x32x16_bf16 v[48:63], v[144:147], v[228:231], v[48:63]
	ds_read_b128 v[144:147], v129 offset:17920
	s_waitcnt lgkmcnt(3)
	v_mfma_f32_32x32x16_bf16 v[32:47], v[148:151], v[228:231], v[32:47]
	ds_read_b128 v[148:151], v129 offset:26112
	s_waitcnt lgkmcnt(3)
	v_mfma_f32_32x32x16_bf16 v[16:31], v[152:155], v[228:231], v[16:31]
	ds_read_b128 v[152:155], v129 offset:50688
	s_waitcnt lgkmcnt(3)
	v_mfma_f32_32x32x16_bf16 v[0:15], v[156:159], v[228:231], v[0:15]
	ds_read_b128 v[156:159], v129 offset:58880
	s_waitcnt vmcnt(1) lgkmcnt(3)
	v_mfma_f32_32x32x16_bf16 v[112:127], v[144:147], v[232:235], v[112:127]
	ds_read_b128 v[144:147], v248 offset:17920
	s_waitcnt lgkmcnt(3)
	v_mfma_f32_32x32x16_bf16 v[96:111], v[148:151], v[232:235], v[96:111]
	ds_read_b128 v[148:151], v248 offset:26112
	s_waitcnt lgkmcnt(3)
; DI unsigned pk2(float lo, float hi) { bf2_t v = __builtin_convertvector((f32x2){lo, hi}, bf2_t); return __builtin_bit_cast(unsigned, v); }
; DI void xattn_unit(const bf16_t* __restrict__ Qg, const bf16_t* __restrict__ Kg, const bf16_t* __restrict__ Vg, bf16_t* __restrict__ Og, lds_t* shm) {
;     ...
;   float mx = S[0][0][0];
; #pragma unroll
;   for (int t = 0; t < 4; ++t)
; #pragma unroll
;     for (int kb = 0; kb < 2; ++kb)
; #pragma unroll
;       for (int i = 0; i < 16; ++i) mx = fmaxf(mx, S[t][kb][i]);
;   { const auto sw = __builtin_amdgcn_permlane32_swap(__float_as_uint(mx), __float_as_uint(mx), false, false); mx = fmaxf(__uint_as_float(sw[0]), __uint_as_float(sw[1])); }
;   float rs = 0.f;
;   bf16x8 P[4][2][2];
; #pragma unroll
;   for (int t = 0; t < 4; ++t)
; #pragma unroll
;     for (int kb = 0; kb < 2; ++kb)
; #pragma unroll
;       for (int s2 = 0; s2 < 2; ++s2) {
;         float e[8];
; #pragma unroll
;         for (int j = 0; j < 8; ++j) { e[j] = __builtin_amdgcn_exp2f(S[t][kb][8 * s2 + j] - mx); rs += e[j]; }
;         u32x4 w; w.x = pk2(e[0], e[1]); w.y = pk2(e[2], e[3]); w.z = pk2(e[4], e[5]); w.w = pk2(e[6], e[7]);
;         P[t][kb][s2] = __builtin_bit_cast(bf16x8, w);
;       }
	v_mfma_f32_32x32x16_bf16 v[80:95], v[152:155], v[232:235], v[80:95]
	ds_read_b128 v[152:155], v248 offset:50688
	s_waitcnt lgkmcnt(3)
	v_mfma_f32_32x32x16_bf16 v[64:79], v[156:159], v[232:235], v[64:79]
	ds_read_b128 v[156:159], v248 offset:58880
	s_waitcnt lgkmcnt(3)
	v_mfma_f32_32x32x16_bf16 v[48:63], v[144:147], v[232:235], v[48:63]
	ds_read_b128 v[144:147], v133 offset:17920
	s_waitcnt lgkmcnt(3)
	v_mfma_f32_32x32x16_bf16 v[32:47], v[148:151], v[232:235], v[32:47]
	ds_read_b128 v[148:151], v133 offset:26112
	s_waitcnt lgkmcnt(3)
	v_mfma_f32_32x32x16_bf16 v[16:31], v[152:155], v[232:235], v[16:31]
	ds_read_b128 v[152:155], v133 offset:50688
	s_waitcnt lgkmcnt(3)
	v_mfma_f32_32x32x16_bf16 v[0:15], v[156:159], v[232:235], v[0:15]
	ds_read_b128 v[156:159], v133 offset:58880
	s_waitcnt vmcnt(0) lgkmcnt(3)
	v_mfma_f32_32x32x16_bf16 v[112:127], v[144:147], v[236:239], v[112:127]
	ds_read_b128 v[144:147], v249 offset:17920
	s_waitcnt lgkmcnt(3)
	v_mfma_f32_32x32x16_bf16 v[96:111], v[148:151], v[236:239], v[96:111]
	ds_read_b128 v[148:151], v249 offset:26112
	s_waitcnt lgkmcnt(3)
	v_mfma_f32_32x32x16_bf16 v[80:95], v[152:155], v[236:239], v[80:95]
	ds_read_b128 v[152:155], v249 offset:50688
	s_waitcnt lgkmcnt(3)
	v_mfma_f32_32x32x16_bf16 v[64:79], v[156:159], v[236:239], v[64:79]
	ds_read_b128 v[156:159], v249 offset:58880
	s_waitcnt lgkmcnt(3)
	v_mfma_f32_32x32x16_bf16 v[48:63], v[144:147], v[236:239], v[48:63]
	s_waitcnt lgkmcnt(2)
	v_mfma_f32_32x32x16_bf16 v[32:47], v[148:151], v[236:239], v[32:47]
	s_waitcnt lgkmcnt(1)
	v_mfma_f32_32x32x16_bf16 v[16:31], v[152:155], v[236:239], v[16:31]
	s_waitcnt lgkmcnt(0)
	v_mfma_f32_32x32x16_bf16 v[0:15], v[156:159], v[236:239], v[0:15]
	v_max_f32_e32 v128, v113, v113
	v_max_f32_e32 v129, v112, v112
	v_max_f32_e32 v128, v129, v128
	v_max3_f32 v128, v128, v114, v115
	v_max3_f32 v128, v128, v116, v117
	v_max3_f32 v128, v128, v118, v119
	v_max3_f32 v128, v128, v120, v121
	v_max3_f32 v128, v128, v122, v123
	v_max3_f32 v128, v128, v124, v125
	v_max3_f32 v128, v128, v126, v127
	v_max3_f32 v128, v128, v96, v97
	v_max3_f32 v128, v128, v98, v99
	v_max3_f32 v128, v128, v100, v101
	v_max3_f32 v128, v128, v102, v103
	v_max3_f32 v128, v128, v104, v105
	v_max3_f32 v128, v128, v106, v107
	v_max3_f32 v128, v128, v108, v109
	v_max3_f32 v128, v128, v110, v111
	v_max3_f32 v128, v128, v80, v81
	v_max3_f32 v128, v128, v82, v83
	v_max3_f32 v128, v128, v84, v85
	v_max3_f32 v128, v128, v86, v87
	v_max3_f32 v128, v128, v88, v89
	v_max3_f32 v128, v128, v90, v91
	v_max3_f32 v128, v128, v92, v93
	v_max3_f32 v128, v128, v94, v95
	v_max3_f32 v128, v128, v64, v65
	v_max3_f32 v128, v128, v66, v67
	v_max3_f32 v128, v128, v68, v69
	v_max3_f32 v128, v128, v70, v71
	v_max3_f32 v128, v128, v72, v73
	v_max3_f32 v128, v128, v74, v75
	v_max3_f32 v128, v128, v76, v77
	v_max3_f32 v128, v128, v78, v79
	v_max3_f32 v128, v128, v48, v49
	v_max3_f32 v128, v128, v50, v51
	v_max3_f32 v128, v128, v52, v53
	v_max3_f32 v128, v128, v54, v55
	v_max3_f32 v128, v128, v56, v57
	v_max3_f32 v128, v128, v58, v59
	v_max3_f32 v128, v128, v60, v61
	v_max3_f32 v128, v128, v62, v63
	v_max3_f32 v128, v128, v32, v33
	v_max3_f32 v128, v128, v34, v35
	v_max3_f32 v128, v128, v36, v37
	v_max3_f32 v128, v128, v38, v39
	v_max3_f32 v128, v128, v40, v41
	v_max3_f32 v128, v128, v42, v43
	v_max3_f32 v128, v128, v44, v45
	v_max3_f32 v128, v128, v46, v47
	v_max3_f32 v128, v128, v16, v17
	v_max3_f32 v128, v128, v18, v19
	v_max3_f32 v128, v128, v20, v21
	v_max3_f32 v128, v128, v22, v23
	v_max3_f32 v128, v128, v24, v25
	v_max3_f32 v128, v128, v26, v27
	v_max3_f32 v128, v128, v28, v29
	v_max3_f32 v128, v128, v30, v31
	v_max3_f32 v128, v128, v0, v1
	v_max3_f32 v128, v128, v2, v3
	v_max3_f32 v128, v128, v4, v5
	v_max3_f32 v128, v128, v6, v7
	v_max3_f32 v128, v128, v8, v9
	v_max3_f32 v128, v128, v10, v11
	v_max3_f32 v128, v128, v12, v13
	v_max3_f32 v128, v128, v14, v15
	v_mov_b32_e32 v129, v128
	s_nop 1
	v_permlane32_swap_b32_e32 v128, v129
	v_max_f32_e32 v129, v129, v129
	v_max_f32_e32 v128, v128, v128
	v_max_f32_e32 v167, v128, v129
	v_sub_f32_e32 v112, v112, v167
	v_exp_f32_e32 v112, v112
	v_sub_f32_e32 v113, v113, v167
	v_exp_f32_e32 v113, v113
	v_sub_f32_e32 v114, v114, v167
	v_exp_f32_e32 v114, v114
	v_sub_f32_e32 v115, v115, v167
	v_exp_f32_e32 v227, v115
	v_sub_f32_e32 v115, v116, v167
	v_add_f32_e32 v128, 0, v112
	v_exp_f32_e32 v115, v115
	v_sub_f32_e32 v116, v117, v167
	v_add_f32_e32 v128, v113, v128
	v_exp_f32_e32 v116, v116
	v_sub_f32_e32 v117, v118, v167
	v_add_f32_e32 v128, v114, v128
	v_exp_f32_e32 v117, v117
	v_sub_f32_e32 v118, v119, v167
	v_add_f32_e32 v128, v227, v128
	v_exp_f32_e32 v118, v118
	v_sub_f32_e32 v120, v120, v167
	v_add_f32_e32 v128, v115, v128
	v_exp_f32_e32 v217, v120
	v_sub_f32_e32 v120, v121, v167
	v_add_f32_e32 v128, v116, v128
	v_exp_f32_e32 v221, v120
	v_sub_f32_e32 v120, v122, v167
	v_add_f32_e32 v128, v117, v128
	v_exp_f32_e32 v210, v120
	v_sub_f32_e32 v120, v123, v167
	v_add_f32_e32 v119, v118, v128
	v_exp_f32_e32 v218, v120
	v_sub_f32_e32 v120, v124, v167
	v_add_f32_e32 v119, v217, v119
	v_exp_f32_e32 v215, v120
	v_sub_f32_e32 v120, v125, v167
	v_add_f32_e32 v119, v221, v119
	v_exp_f32_e32 v220, v120
	v_sub_f32_e32 v120, v126, v167
	v_add_f32_e32 v119, v210, v119
	v_exp_f32_e32 v208, v120
	v_sub_f32_e32 v120, v127, v167
	v_add_f32_e32 v119, v218, v119
	v_exp_f32_e32 v216, v120
	v_sub_f32_e32 v96, v96, v167
	v_add_f32_e32 v119, v215, v119
	v_exp_f32_e32 v197, v96
	v_sub_f32_e32 v97, v97, v167
	v_add_f32_e32 v119, v220, v119
	v_exp_f32_e32 v201, v97
	v_sub_f32_e32 v97, v98, v167
	v_add_f32_e32 v119, v208, v119
	v_exp_f32_e32 v194, v97
; DI unsigned pk2(float lo, float hi) { bf2_t v = __builtin_convertvector((f32x2){lo, hi}, bf2_t); return __builtin_bit_cast(unsigned, v); }
; DI void xattn_unit(const bf16_t* __restrict__ Qg, const bf16_t* __restrict__ Kg, const bf16_t* __restrict__ Vg, bf16_t* __restrict__ Og, lds_t* shm) {
;     ...
; #pragma unroll
;   for (int t = 0; t < 4; ++t)
; #pragma unroll
;     for (int kb = 0; kb < 2; ++kb)
; #pragma unroll
;       for (int s2 = 0; s2 < 2; ++s2) {
;         float e[8];
; #pragma unroll
;         for (int j = 0; j < 8; ++j) { e[j] = __builtin_amdgcn_exp2f(S[t][kb][8 * s2 + j] - mx); rs += e[j]; }
;         u32x4 w; w.x = pk2(e[0], e[1]); w.y = pk2(e[2], e[3]); w.z = pk2(e[4], e[5]); w.w = pk2(e[6], e[7]);
;         P[t][kb][s2] = __builtin_bit_cast(bf16x8, w);
;       }
	v_sub_f32_e32 v97, v99, v167
	v_add_f32_e32 v119, v216, v119
	v_exp_f32_e32 v198, v97
	v_sub_f32_e32 v97, v100, v167
	v_add_f32_e32 v96, v197, v119
	v_exp_f32_e32 v195, v97
	v_sub_f32_e32 v97, v101, v167
	v_add_f32_e32 v96, v201, v96
	v_exp_f32_e32 v199, v97
	v_sub_f32_e32 v97, v102, v167
	v_add_f32_e32 v96, v194, v96
	v_exp_f32_e32 v191, v97
	v_sub_f32_e32 v97, v103, v167
	v_add_f32_e32 v96, v198, v96
	v_exp_f32_e32 v193, v97
	v_sub_f32_e32 v97, v104, v167
	v_add_f32_e32 v96, v195, v96
	v_exp_f32_e32 v179, v97
	v_sub_f32_e32 v97, v105, v167
	v_add_f32_e32 v96, v199, v96
	v_exp_f32_e32 v183, v97
	v_sub_f32_e32 v97, v106, v167
	v_add_f32_e32 v96, v191, v96
	v_exp_f32_e32 v177, v97
	v_sub_f32_e32 v97, v107, v167
	v_add_f32_e32 v96, v193, v96
	v_exp_f32_e32 v180, v97
	v_sub_f32_e32 v97, v108, v167
	v_add_f32_e32 v96, v179, v96
	v_exp_f32_e32 v178, v97
	v_sub_f32_e32 v97, v109, v167
	v_add_f32_e32 v96, v183, v96
	v_exp_f32_e32 v181, v97
	v_sub_f32_e32 v97, v110, v167
	v_add_f32_e32 v96, v177, v96
	v_exp_f32_e32 v174, v97
	v_sub_f32_e32 v97, v111, v167
	v_add_f32_e32 v96, v180, v96
	v_exp_f32_e32 v176, v97
	v_sub_f32_e32 v80, v80, v167
	v_add_f32_e32 v96, v178, v96
	v_exp_f32_e32 v80, v80
	v_sub_f32_e32 v81, v81, v167
	v_add_f32_e32 v96, v181, v96
	v_exp_f32_e32 v81, v81
	v_sub_f32_e32 v82, v82, v167
	v_add_f32_e32 v96, v174, v96
	v_exp_f32_e32 v82, v82
	v_sub_f32_e32 v83, v83, v167
	v_add_f32_e32 v96, v176, v96
	v_exp_f32_e32 v83, v83
	v_sub_f32_e32 v84, v84, v167
	v_add_f32_e32 v96, v80, v96
	v_exp_f32_e32 v84, v84
	v_sub_f32_e32 v85, v85, v167
	v_add_f32_e32 v96, v81, v96
	v_exp_f32_e32 v85, v85
	v_sub_f32_e32 v86, v86, v167
	v_add_f32_e32 v96, v82, v96
	v_exp_f32_e32 v86, v86
	v_sub_f32_e32 v87, v87, v167
	v_add_f32_e32 v96, v83, v96
	v_exp_f32_e32 v87, v87
	v_cvt_pk_bf16_f32 v128, v80, v81
	v_sub_f32_e32 v80, v88, v167
	v_add_f32_e32 v96, v84, v96
	v_cvt_pk_bf16_f32 v129, v82, v83
	v_exp_f32_e32 v80, v80
	v_sub_f32_e32 v82, v89, v167
	v_add_f32_e32 v96, v85, v96
	v_exp_f32_e32 v82, v82
	v_sub_f32_e32 v83, v90, v167
	v_add_f32_e32 v96, v86, v96
	v_cvt_pk_bf16_f32 v130, v84, v85
	v_exp_f32_e32 v83, v83
	v_sub_f32_e32 v84, v91, v167
	v_add_f32_e32 v96, v87, v96
	v_exp_f32_e32 v84, v84
	v_sub_f32_e32 v85, v92, v167
	v_cvt_pk_bf16_f32 v131, v86, v87
	v_add_f32_e32 v81, v80, v96
	v_exp_f32_e32 v85, v85
	v_sub_f32_e32 v86, v93, v167
	v_add_f32_e32 v81, v82, v81
	v_exp_f32_e32 v86, v86
	v_sub_f32_e32 v87, v94, v167
	v_add_f32_e32 v81, v83, v81
	v_exp_f32_e32 v87, v87
	v_sub_f32_e32 v88, v95, v167
	v_add_f32_e32 v81, v84, v81
	v_exp_f32_e32 v88, v88
	v_sub_f32_e32 v64, v64, v167
	v_add_f32_e32 v81, v85, v81
	v_exp_f32_e32 v64, v64
	v_sub_f32_e32 v65, v65, v167
	v_add_f32_e32 v81, v86, v81
	v_exp_f32_e32 v65, v65
	v_sub_f32_e32 v66, v66, v167
	v_add_f32_e32 v81, v87, v81
	v_exp_f32_e32 v66, v66
	v_sub_f32_e32 v67, v67, v167
	v_add_f32_e32 v81, v88, v81
	v_exp_f32_e32 v67, v67
	v_sub_f32_e32 v68, v68, v167
	v_cvt_pk_bf16_f32 v132, v80, v82
	v_add_f32_e32 v80, v64, v81
	v_exp_f32_e32 v68, v68
	v_sub_f32_e32 v69, v69, v167
	v_add_f32_e32 v80, v65, v80
	v_exp_f32_e32 v69, v69
	v_sub_f32_e32 v70, v70, v167
	v_add_f32_e32 v80, v66, v80
	v_exp_f32_e32 v70, v70
	v_sub_f32_e32 v71, v71, v167
	v_add_f32_e32 v80, v67, v80
	v_exp_f32_e32 v71, v71
	v_cvt_pk_bf16_f32 v136, v64, v65
	v_sub_f32_e32 v64, v72, v167
	v_add_f32_e32 v80, v68, v80
	v_cvt_pk_bf16_f32 v137, v66, v67
	v_exp_f32_e32 v64, v64
	v_sub_f32_e32 v66, v73, v167
	v_add_f32_e32 v80, v69, v80
	v_exp_f32_e32 v66, v66
	v_sub_f32_e32 v67, v74, v167
	v_add_f32_e32 v80, v70, v80
	v_cvt_pk_bf16_f32 v138, v68, v69
	v_exp_f32_e32 v67, v67
	v_sub_f32_e32 v68, v75, v167
	v_add_f32_e32 v80, v71, v80
	v_exp_f32_e32 v68, v68
	v_sub_f32_e32 v69, v76, v167
	v_cvt_pk_bf16_f32 v139, v70, v71
	v_add_f32_e32 v65, v64, v80
	v_exp_f32_e32 v69, v69
	v_sub_f32_e32 v70, v77, v167
	v_add_f32_e32 v65, v66, v65
	v_exp_f32_e32 v70, v70
	v_sub_f32_e32 v71, v78, v167
	v_add_f32_e32 v65, v67, v65
	v_exp_f32_e32 v71, v71
	v_sub_f32_e32 v72, v79, v167
	v_add_f32_e32 v65, v68, v65
	v_exp_f32_e32 v72, v72
	v_sub_f32_e32 v48, v48, v167
	v_add_f32_e32 v65, v69, v65
	v_exp_f32_e32 v48, v48
	v_sub_f32_e32 v49, v49, v167
	v_add_f32_e32 v65, v70, v65
	v_exp_f32_e32 v49, v49
	v_sub_f32_e32 v50, v50, v167
	v_add_f32_e32 v65, v71, v65
	v_exp_f32_e32 v50, v50
	v_sub_f32_e32 v51, v51, v167
	v_add_f32_e32 v65, v72, v65
	v_exp_f32_e32 v51, v51
	v_sub_f32_e32 v52, v52, v167
	v_cvt_pk_bf16_f32 v156, v64, v66
	v_add_f32_e32 v64, v48, v65
	v_exp_f32_e32 v52, v52
	v_sub_f32_e32 v53, v53, v167
	v_add_f32_e32 v64, v49, v64
	v_exp_f32_e32 v53, v53
	v_sub_f32_e32 v54, v54, v167
	v_add_f32_e32 v64, v50, v64
	v_exp_f32_e32 v54, v54
	v_sub_f32_e32 v55, v55, v167
	v_add_f32_e32 v64, v51, v64
	v_exp_f32_e32 v55, v55
	v_cvt_pk_bf16_f32 v152, v48, v49
	v_sub_f32_e32 v48, v56, v167
	v_add_f32_e32 v64, v52, v64
	v_cvt_pk_bf16_f32 v153, v50, v51
	v_exp_f32_e32 v48, v48
	v_sub_f32_e32 v50, v57, v167
	v_add_f32_e32 v64, v53, v64
	v_exp_f32_e32 v50, v50
	v_sub_f32_e32 v51, v58, v167
	v_add_f32_e32 v64, v54, v64
	v_cvt_pk_bf16_f32 v154, v52, v53
	v_exp_f32_e32 v51, v51
	v_sub_f32_e32 v52, v59, v167
	v_add_f32_e32 v64, v55, v64
	v_exp_f32_e32 v52, v52
	v_sub_f32_e32 v53, v60, v167
	v_cvt_pk_bf16_f32 v155, v54, v55
	v_add_f32_e32 v49, v48, v64
	v_exp_f32_e32 v53, v53
	v_sub_f32_e32 v54, v61, v167
	v_add_f32_e32 v49, v50, v49
	v_exp_f32_e32 v54, v54
	v_sub_f32_e32 v55, v62, v167
	v_add_f32_e32 v49, v51, v49
	v_exp_f32_e32 v55, v55
	v_sub_f32_e32 v56, v63, v167
	v_add_f32_e32 v49, v52, v49
	v_exp_f32_e32 v56, v56
	v_sub_f32_e32 v32, v32, v167
	v_add_f32_e32 v49, v53, v49
; DI unsigned pk2(float lo, float hi) { bf2_t v = __builtin_convertvector((f32x2){lo, hi}, bf2_t); return __builtin_bit_cast(unsigned, v); }
; DI void xattn_unit(const bf16_t* __restrict__ Qg, const bf16_t* __restrict__ Kg, const bf16_t* __restrict__ Vg, bf16_t* __restrict__ Og, lds_t* shm) {
;     ...
; #pragma unroll
;   for (int t = 0; t < 4; ++t)
; #pragma unroll
;     for (int kb = 0; kb < 2; ++kb)
; #pragma unroll
;       for (int s2 = 0; s2 < 2; ++s2) {
;         float e[8];
; #pragma unroll
;         for (int j = 0; j < 8; ++j) { e[j] = __builtin_amdgcn_exp2f(S[t][kb][8 * s2 + j] - mx); rs += e[j]; }
;         u32x4 w; w.x = pk2(e[0], e[1]); w.y = pk2(e[2], e[3]); w.z = pk2(e[4], e[5]); w.w = pk2(e[6], e[7]);
;         P[t][kb][s2] = __builtin_bit_cast(bf16x8, w);
;       }
;   const float l = rs + __shfl_xor(rs, 32);
;   __builtin_amdgcn_sched_barrier(0);
;   __syncthreads();
;   __builtin_amdgcn_sched_barrier(0);
	v_exp_f32_e32 v32, v32
	v_sub_f32_e32 v33, v33, v167
	v_add_f32_e32 v49, v54, v49
	v_exp_f32_e32 v33, v33
	v_sub_f32_e32 v34, v34, v167
	v_add_f32_e32 v49, v55, v49
	v_exp_f32_e32 v34, v34
	v_sub_f32_e32 v35, v35, v167
	v_add_f32_e32 v49, v56, v49
	v_exp_f32_e32 v35, v35
	v_sub_f32_e32 v36, v36, v167
	v_cvt_pk_bf16_f32 v148, v48, v50
	v_add_f32_e32 v48, v32, v49
	v_exp_f32_e32 v36, v36
	v_sub_f32_e32 v37, v37, v167
	v_add_f32_e32 v48, v33, v48
	v_exp_f32_e32 v37, v37
	v_sub_f32_e32 v38, v38, v167
	v_add_f32_e32 v48, v34, v48
	v_exp_f32_e32 v38, v38
	v_sub_f32_e32 v39, v39, v167
	v_add_f32_e32 v48, v35, v48
	v_exp_f32_e32 v39, v39
	v_cvt_pk_bf16_f32 v140, v32, v33
	v_sub_f32_e32 v32, v40, v167
	v_add_f32_e32 v48, v36, v48
	v_cvt_pk_bf16_f32 v141, v34, v35
	v_exp_f32_e32 v32, v32
	v_sub_f32_e32 v34, v41, v167
	v_add_f32_e32 v48, v37, v48
	v_exp_f32_e32 v34, v34
	v_sub_f32_e32 v35, v42, v167
	v_add_f32_e32 v48, v38, v48
	v_cvt_pk_bf16_f32 v142, v36, v37
	v_exp_f32_e32 v35, v35
	v_sub_f32_e32 v36, v43, v167
	v_add_f32_e32 v48, v39, v48
	v_exp_f32_e32 v36, v36
	v_sub_f32_e32 v37, v44, v167
	v_cvt_pk_bf16_f32 v143, v38, v39
	v_add_f32_e32 v33, v32, v48
	v_exp_f32_e32 v37, v37
	v_sub_f32_e32 v38, v45, v167
	v_add_f32_e32 v33, v34, v33
	v_exp_f32_e32 v38, v38
	v_sub_f32_e32 v39, v46, v167
	v_add_f32_e32 v33, v35, v33
	v_exp_f32_e32 v39, v39
	v_sub_f32_e32 v40, v47, v167
	v_add_f32_e32 v33, v36, v33
	v_exp_f32_e32 v40, v40
	v_sub_f32_e32 v16, v16, v167
	v_add_f32_e32 v33, v37, v33
	v_exp_f32_e32 v171, v16
	v_sub_f32_e32 v17, v17, v167
	v_add_f32_e32 v33, v38, v33
	v_exp_f32_e32 v172, v17
	v_sub_f32_e32 v17, v18, v167
	v_add_f32_e32 v33, v39, v33
	v_exp_f32_e32 v173, v17
	v_sub_f32_e32 v17, v19, v167
	v_add_f32_e32 v33, v40, v33
	v_exp_f32_e32 v175, v17
	v_sub_f32_e32 v17, v20, v167
	v_add_f32_e32 v16, v171, v33
	v_exp_f32_e32 v182, v17
	v_sub_f32_e32 v17, v21, v167
	v_add_f32_e32 v16, v172, v16
	v_exp_f32_e32 v184, v17
	v_sub_f32_e32 v17, v22, v167
	v_add_f32_e32 v16, v173, v16
	v_exp_f32_e32 v185, v17
	v_sub_f32_e32 v17, v23, v167
	v_add_f32_e32 v16, v175, v16
	v_exp_f32_e32 v186, v17
	v_sub_f32_e32 v17, v24, v167
	v_add_f32_e32 v16, v182, v16
	v_exp_f32_e32 v187, v17
	v_sub_f32_e32 v17, v25, v167
	v_add_f32_e32 v16, v184, v16
	v_exp_f32_e32 v188, v17
	v_sub_f32_e32 v17, v26, v167
	v_add_f32_e32 v16, v185, v16
	v_exp_f32_e32 v189, v17
	v_sub_f32_e32 v17, v27, v167
	v_add_f32_e32 v16, v186, v16
	v_exp_f32_e32 v190, v17
	v_sub_f32_e32 v17, v28, v167
	v_add_f32_e32 v16, v187, v16
	v_exp_f32_e32 v192, v17
	v_sub_f32_e32 v17, v29, v167
	v_add_f32_e32 v16, v188, v16
	v_exp_f32_e32 v196, v17
	v_sub_f32_e32 v17, v30, v167
	v_add_f32_e32 v16, v189, v16
	v_exp_f32_e32 v200, v17
	v_sub_f32_e32 v17, v31, v167
	v_add_f32_e32 v16, v190, v16
	v_exp_f32_e32 v202, v17
	v_sub_f32_e32 v0, v0, v167
	v_add_f32_e32 v16, v192, v16
	v_exp_f32_e32 v203, v0
	v_sub_f32_e32 v1, v1, v167
	v_add_f32_e32 v16, v196, v16
	v_exp_f32_e32 v204, v1
	v_sub_f32_e32 v1, v2, v167
	v_add_f32_e32 v16, v200, v16
	v_exp_f32_e32 v205, v1
	v_sub_f32_e32 v1, v3, v167
	v_add_f32_e32 v16, v202, v16
	v_exp_f32_e32 v206, v1
	v_sub_f32_e32 v1, v4, v167
	v_add_f32_e32 v0, v203, v16
	v_exp_f32_e32 v207, v1
	v_sub_f32_e32 v1, v5, v167
	v_add_f32_e32 v0, v204, v0
	v_exp_f32_e32 v209, v1
	v_sub_f32_e32 v1, v6, v167
	v_add_f32_e32 v0, v205, v0
	v_exp_f32_e32 v211, v1
	v_sub_f32_e32 v1, v7, v167
	v_add_f32_e32 v0, v206, v0
	v_exp_f32_e32 v219, v1
	v_sub_f32_e32 v1, v8, v167
	v_add_f32_e32 v0, v207, v0
	v_exp_f32_e32 v222, v1
	v_sub_f32_e32 v1, v9, v167
	v_add_f32_e32 v0, v209, v0
	v_exp_f32_e32 v223, v1
	v_sub_f32_e32 v1, v10, v167
	v_add_f32_e32 v0, v211, v0
	v_exp_f32_e32 v224, v1
	v_sub_f32_e32 v1, v11, v167
	v_add_f32_e32 v0, v219, v0
	v_exp_f32_e32 v225, v1
	v_sub_f32_e32 v1, v12, v167
	v_add_f32_e32 v0, v222, v0
	v_exp_f32_e32 v226, v1
	v_sub_f32_e32 v1, v13, v167
	v_add_f32_e32 v0, v223, v0
	v_exp_f32_e32 v228, v1
	v_sub_f32_e32 v1, v14, v167
	v_add_f32_e32 v0, v224, v0
	v_exp_f32_e32 v229, v1
	v_sub_f32_e32 v1, v15, v167
	v_add_f32_e32 v0, v225, v0
	v_exp_f32_e32 v230, v1
	v_add_f32_e32 v0, v226, v0
	v_add_f32_e32 v0, v228, v0
	v_add_f32_e32 v0, v229, v0
	v_add_f32_e32 v167, v230, v0
	v_cvt_pk_bf16_f32 v133, v83, v84
	v_cvt_pk_bf16_f32 v134, v85, v86
	v_cvt_pk_bf16_f32 v135, v87, v88
	v_cvt_pk_bf16_f32 v157, v67, v68
	v_cvt_pk_bf16_f32 v158, v69, v70
	v_cvt_pk_bf16_f32 v159, v71, v72
	v_cvt_pk_bf16_f32 v149, v51, v52
	v_cvt_pk_bf16_f32 v150, v53, v54
	v_cvt_pk_bf16_f32 v151, v55, v56
	v_cvt_pk_bf16_f32 v144, v32, v34
	v_cvt_pk_bf16_f32 v145, v35, v36
	v_cvt_pk_bf16_f32 v146, v37, v38
	v_cvt_pk_bf16_f32 v147, v39, v40
	ds_bpermute_b32 v168, v213, v167
	s_waitcnt lgkmcnt(0)
	s_barrier
; #define MFMA32(a, b, c) __builtin_amdgcn_mfma_f32_32x32x16_bf16((a), (b), (c), 0, 0, 0)
; DI void xattn_unit(const bf16_t* __restrict__ Qg, const bf16_t* __restrict__ Kg, const bf16_t* __restrict__ Vg, bf16_t* __restrict__ Og, lds_t* shm) {
;     ...
; #pragma unroll
;   for (int t = 1; t < 4; ++t) issue_tile(Vg, t, t * 32768);
;   f32x16 O[NC];
; #pragma unroll
;   for (int c = 0; c < NC; ++c)
; #pragma unroll
;     for (int i = 0; i < 16; ++i) O[c][i] = 0.f;
; #pragma unroll
;   for (int t = 0; t < 4; ++t) {
;     if (t == 1) { __builtin_amdgcn_sched_barrier(0); asm volatile("s_waitcnt vmcnt(0)" ::: "memory"); __syncthreads(); __builtin_amdgcn_sched_barrier(0); }
;     const unsigned vbase = (t == 0) ? 131072u : (unsigned)t * 32768u;
; #pragma unroll
;     for (int ks = 0; ks < 4; ++ks)
; #pragma unroll
;       for (int c = 0; c < NC; ++c) {
;         const unsigned vo = vbase + (c >> 2) * 16384 + 512 * (c & 3) + 4096 * ks;
;         const bf16x8 vf = tr_pair(shm + vo + va0, shm + vo + 2048 + va1);
;         O[c] = MFMA32(vf, P[t][ks >> 1][ks & 1], O[c]);
;       }
	s_add_u32 s38, s36, 0x40800
	s_mov_b32 m0, s67
	s_addc_u32 s39, s37, 0
	global_load_lds_dwordx4 v160, s[38:39]
	s_mov_b32 m0, s0
	v_add_u32_e32 v2, s14, v170
	global_load_lds_dwordx4 v162, s[38:39]
	s_add_u32 s38, s36, 0x40900
	s_addc_u32 s39, s37, 0
	s_mov_b32 m0, s1
	s_add_u32 s0, s36, 0x80800
	global_load_lds_dwordx4 v160, s[38:39]
	s_mov_b32 m0, vcc_lo
	s_addc_u32 s1, s37, 0
	global_load_lds_dwordx4 v162, s[38:39]
	s_mov_b32 m0, vcc_hi
	v_cvt_pk_bf16_f32 v0, v112, v113
	global_load_lds_dwordx4 v160, s[0:1]
	s_mov_b32 m0, s28
	v_cvt_pk_bf16_f32 v1, v114, v227
	global_load_lds_dwordx4 v162, s[0:1]
	s_add_u32 s0, s36, 0x80900
	s_addc_u32 s1, s37, 0
	s_mov_b32 m0, s29
	v_cvt_pk_bf16_f32 v232, v217, v221
	global_load_lds_dwordx4 v160, s[0:1]
	s_mov_b32 m0, s68
	v_cvt_pk_bf16_f32 v233, v210, v218
	global_load_lds_dwordx4 v162, s[0:1]
	s_add_u32 s0, s36, 0xc0800
	s_addc_u32 s1, s37, 0
	s_mov_b32 m0, s69
	v_cvt_pk_bf16_f32 v234, v215, v220
	global_load_lds_dwordx4 v160, s[0:1]
	s_mov_b32 m0, s76
	v_cvt_pk_bf16_f32 v235, v208, v216
	global_load_lds_dwordx4 v162, s[0:1]
	s_add_u32 s0, s36, 0xc0900
	s_addc_u32 s1, s37, 0
	s_mov_b32 m0, s77
	s_nop 0
	global_load_lds_dwordx4 v160, s[0:1]
	s_mov_b32 m0, s78
	v_and_b32_e32 v160, 8, v169
	global_load_lds_dwordx4 v162, s[0:1]
	v_readlane_b32 s0, v254, 14
	v_add3_u32 v2, v2, v166, v160
	s_nop 0
	v_add_u32_e32 v3, s0, v170
	v_add3_u32 v3, v3, v165, v160
	ds_read_b64_tr_b16 v[4:5], v2
	ds_read_b64_tr_b16 v[6:7], v3
	v_readlane_b32 s0, v254, 25
	v_cvt_pk_bf16_f32 v2, v115, v116
	v_cvt_pk_bf16_f32 v3, v117, v118
	v_add_u32_e32 v8, s0, v170
	v_readlane_b32 s0, v254, 26
	v_add3_u32 v8, v8, v166, v160
	s_waitcnt lgkmcnt(0)
	v_mfma_f32_32x32x16_bf16 v[112:127], v[4:7], v[0:3], 0
	v_add_u32_e32 v9, s0, v170
	v_readlane_b32 s0, v254, 27
	v_add3_u32 v10, v9, v165, v160
	ds_read_b64_tr_b16 v[8:9], v8
	ds_read_b64_tr_b16 v[10:11], v10
	v_add_u32_e32 v4, s0, v170
	v_readlane_b32 s0, v254, 28
	v_add3_u32 v4, v4, v166, v160
	s_waitcnt lgkmcnt(0)
	v_mfma_f32_32x32x16_bf16 v[96:111], v[8:11], v[0:3], 0
	v_add_u32_e32 v5, s0, v170
	v_add3_u32 v6, v5, v165, v160
	ds_read_b64_tr_b16 v[4:5], v4
	ds_read_b64_tr_b16 v[6:7], v6
	v_readlane_b32 s0, v254, 29
	s_nop 1
	v_add_u32_e32 v8, s0, v170
	v_readlane_b32 s0, v254, 30
	v_add3_u32 v8, v8, v166, v160
	s_waitcnt lgkmcnt(0)
	v_mfma_f32_32x32x16_bf16 v[80:95], v[4:7], v[0:3], 0
	v_add_u32_e32 v9, s0, v170
	v_readlane_b32 s0, v254, 31
	v_add3_u32 v10, v9, v165, v160
	ds_read_b64_tr_b16 v[8:9], v8
	ds_read_b64_tr_b16 v[10:11], v10
	v_add_u32_e32 v4, s0, v170
	v_readlane_b32 s0, v254, 32
	v_add3_u32 v4, v4, v166, v160
	s_waitcnt lgkmcnt(0)
	v_mfma_f32_32x32x16_bf16 v[64:79], v[8:11], v[0:3], 0
	v_add_u32_e32 v5, s0, v170
	v_add3_u32 v6, v5, v165, v160
	ds_read_b64_tr_b16 v[4:5], v4
	ds_read_b64_tr_b16 v[6:7], v6
	v_readlane_b32 s0, v254, 33
	s_nop 1
	v_add_u32_e32 v8, s0, v170
	v_readlane_b32 s0, v254, 34
	v_add3_u32 v8, v8, v166, v160
	s_waitcnt lgkmcnt(0)
	v_mfma_f32_32x32x16_bf16 v[48:63], v[4:7], v[0:3], 0
	v_add_u32_e32 v9, s0, v170
	v_readlane_b32 s0, v254, 35
	v_add3_u32 v10, v9, v165, v160
	ds_read_b64_tr_b16 v[8:9], v8
	ds_read_b64_tr_b16 v[10:11], v10
	v_add_u32_e32 v4, s0, v170
	v_readlane_b32 s0, v254, 36
	v_add3_u32 v4, v4, v166, v160
	s_waitcnt lgkmcnt(0)
	v_mfma_f32_32x32x16_bf16 v[32:47], v[8:11], v[0:3], 0
	v_add_u32_e32 v5, s0, v170
	v_add3_u32 v6, v5, v165, v160
	ds_read_b64_tr_b16 v[4:5], v4
	ds_read_b64_tr_b16 v[6:7], v6
	v_readlane_b32 s0, v254, 37
	s_nop 1
	v_add_u32_e32 v8, s0, v170
	v_readlane_b32 s0, v254, 38
	s_waitcnt lgkmcnt(0)
	v_mfma_f32_32x32x16_bf16 v[16:31], v[4:7], v[0:3], 0
	v_add3_u32 v8, v8, v166, v160
	v_add_u32_e32 v9, s0, v170
	v_readlane_b32 s0, v254, 39
	v_add3_u32 v10, v9, v165, v160
	ds_read_b64_tr_b16 v[8:9], v8
	ds_read_b64_tr_b16 v[10:11], v10
	v_add_u32_e32 v4, s0, v170
	v_readlane_b32 s0, v254, 40
	v_add3_u32 v4, v4, v166, v160
	s_nop 0
	v_add_u32_e32 v5, s0, v170
	v_readlane_b32 s0, v254, 41
	v_add3_u32 v5, v5, v165, v160
	ds_read_b64_tr_b16 v[236:237], v4
	ds_read_b64_tr_b16 v[238:239], v5
	v_add_u32_e32 v162, s0, v170
	v_readlane_b32 s0, v254, 42
	v_add3_u32 v162, v162, v166, v160
	s_waitcnt lgkmcnt(0)
	v_mfma_f32_32x32x16_bf16 v[112:127], v[236:239], v[232:235], v[112:127]
	v_add_u32_e32 v169, s0, v170
	v_add3_u32 v169, v169, v165, v160
	ds_read_b64_tr_b16 v[240:241], v162
	ds_read_b64_tr_b16 v[242:243], v169
	v_readlane_b32 s0, v254, 43
	s_nop 1
	v_add_u32_e32 v162, s0, v170
	v_readlane_b32 s0, v254, 44
	v_add3_u32 v162, v162, v166, v160
	s_waitcnt lgkmcnt(0)
	v_mfma_f32_32x32x16_bf16 v[96:111], v[240:243], v[232:235], v[96:111]
	v_add_u32_e32 v169, s0, v170
	v_readlane_b32 s0, v254, 45
	v_add3_u32 v169, v169, v165, v160
	ds_read_b64_tr_b16 v[236:237], v162
	ds_read_b64_tr_b16 v[238:239], v169
	v_add_u32_e32 v162, s0, v170
	v_readlane_b32 s0, v254, 46
	v_add3_u32 v162, v162, v166, v160
	s_waitcnt lgkmcnt(0)
	v_mfma_f32_32x32x16_bf16 v[80:95], v[236:239], v[232:235], v[80:95]
	v_add_u32_e32 v169, s0, v170
	v_add3_u32 v169, v169, v165, v160
	ds_read_b64_tr_b16 v[240:241], v162
	ds_read_b64_tr_b16 v[242:243], v169
	v_readlane_b32 s0, v254, 47
	s_nop 1
	v_add_u32_e32 v162, s0, v170
	v_readlane_b32 s0, v254, 48
	v_add3_u32 v162, v162, v166, v160
	s_waitcnt lgkmcnt(0)
	v_mfma_f32_32x32x16_bf16 v[64:79], v[240:243], v[232:235], v[64:79]
	v_add_u32_e32 v169, s0, v170
	v_readlane_b32 s0, v254, 49
	v_add3_u32 v169, v169, v165, v160
	ds_read_b64_tr_b16 v[236:237], v162
	ds_read_b64_tr_b16 v[238:239], v169
	v_add_u32_e32 v162, s0, v170
	v_readlane_b32 s0, v254, 50
	v_add3_u32 v162, v162, v166, v160
	v_mfma_f32_32x32x16_bf16 v[0:15], v[8:11], v[0:3], 0
	v_add_u32_e32 v169, s0, v170
	v_add3_u32 v169, v169, v165, v160
	ds_read_b64_tr_b16 v[240:241], v162
	ds_read_b64_tr_b16 v[242:243], v169
	v_readlane_b32 s0, v254, 51
	s_nop 1
	v_add_u32_e32 v162, s0, v170
	v_readlane_b32 s0, v254, 52
	v_add3_u32 v162, v162, v166, v160
	s_waitcnt lgkmcnt(0)
; #define MFMA32(a, b, c) __builtin_amdgcn_mfma_f32_32x32x16_bf16((a), (b), (c), 0, 0, 0)
; DI void xattn_unit(const bf16_t* __restrict__ Qg, const bf16_t* __restrict__ Kg, const bf16_t* __restrict__ Vg, bf16_t* __restrict__ Og, lds_t* shm) {
;     ...
; #pragma unroll
;   for (int t = 0; t < 4; ++t) {
;     if (t == 1) { __builtin_amdgcn_sched_barrier(0); asm volatile("s_waitcnt vmcnt(0)" ::: "memory"); __syncthreads(); __builtin_amdgcn_sched_barrier(0); }
;     const unsigned vbase = (t == 0) ? 131072u : (unsigned)t * 32768u;
; #pragma unroll
;     for (int ks = 0; ks < 4; ++ks)
; #pragma unroll
;       for (int c = 0; c < NC; ++c) {
;         const unsigned vo = vbase + (c >> 2) * 16384 + 512 * (c & 3) + 4096 * ks;
;         const bf16x8 vf = tr_pair(shm + vo + va0, shm + vo + 2048 + va1);
;         O[c] = MFMA32(vf, P[t][ks >> 1][ks & 1], O[c]);
;       }
	v_mfma_f32_32x32x16_bf16 v[32:47], v[240:243], v[232:235], v[32:47]
	v_add_u32_e32 v169, s0, v170
	v_readlane_b32 s0, v254, 53
	v_add3_u32 v169, v169, v165, v160
	ds_read_b64_tr_b16 v[244:245], v162
	ds_read_b64_tr_b16 v[246:247], v169
	v_add_u32_e32 v162, s0, v170
	v_readlane_b32 s0, v254, 54
	v_add3_u32 v162, v162, v166, v160
	s_waitcnt lgkmcnt(0)
	v_mfma_f32_32x32x16_bf16 v[16:31], v[244:247], v[232:235], v[16:31]
	v_add_u32_e32 v169, s0, v170
	v_add3_u32 v169, v169, v165, v160
	ds_read_b64_tr_b16 v[240:241], v162
	ds_read_b64_tr_b16 v[242:243], v169
	v_readlane_b32 s0, v254, 55
	s_nop 1
	v_add_u32_e32 v162, s0, v170
	v_readlane_b32 s0, v254, 56
	v_add3_u32 v162, v162, v166, v160
	v_mfma_f32_32x32x16_bf16 v[48:63], v[236:239], v[232:235], v[48:63]
	v_add_u32_e32 v169, s0, v170
	v_readlane_b32 s0, v254, 57
	v_add3_u32 v169, v169, v165, v160
	ds_read_b64_tr_b16 v[244:245], v162
	ds_read_b64_tr_b16 v[246:247], v169
	v_add_u32_e32 v162, s0, v170
	v_readlane_b32 s0, v254, 58
	v_add3_u32 v162, v162, v166, v160
	s_waitcnt lgkmcnt(0)
	v_mfma_f32_32x32x16_bf16 v[0:15], v[240:243], v[232:235], v[0:15]
	v_add_u32_e32 v169, s0, v170
	v_add3_u32 v169, v169, v165, v160
	ds_read_b64_tr_b16 v[232:233], v162
	ds_read_b64_tr_b16 v[234:235], v169
	v_readlane_b32 s0, v254, 59
	v_cvt_pk_bf16_f32 v236, v197, v201
	v_cvt_pk_bf16_f32 v237, v194, v198
	v_add_u32_e32 v162, s0, v170
	v_readlane_b32 s0, v254, 60
	v_cvt_pk_bf16_f32 v238, v195, v199
	v_cvt_pk_bf16_f32 v239, v191, v193
	v_add3_u32 v162, v162, v166, v160
	v_add_u32_e32 v169, s0, v170
	v_readlane_b32 s0, v254, 61
	s_waitcnt lgkmcnt(0)
	v_mfma_f32_32x32x16_bf16 v[96:111], v[232:235], v[236:239], v[96:111]
	v_add3_u32 v169, v169, v165, v160
	ds_read_b64_tr_b16 v[232:233], v162
	ds_read_b64_tr_b16 v[234:235], v169
	v_add_u32_e32 v162, s0, v170
	v_readlane_b32 s0, v254, 62
	v_add3_u32 v162, v162, v166, v160
	s_nop 0
	v_add_u32_e32 v169, s0, v170
	v_add3_u32 v169, v169, v165, v160
	ds_read_b64_tr_b16 v[240:241], v162
	ds_read_b64_tr_b16 v[242:243], v169
	v_readlane_b32 s0, v254, 63
	s_waitcnt lgkmcnt(0)
	v_mfma_f32_32x32x16_bf16 v[80:95], v[232:235], v[236:239], v[80:95]
	v_add_u32_e32 v162, s0, v170
	v_readlane_b32 s0, v255, 0
	v_add3_u32 v162, v162, v166, v160
	s_nop 0
	v_add_u32_e32 v169, s0, v170
	v_readlane_b32 s0, v255, 1
	v_add3_u32 v169, v169, v165, v160
	ds_read_b64_tr_b16 v[232:233], v162
	ds_read_b64_tr_b16 v[234:235], v169
	v_add_u32_e32 v162, s0, v170
	v_readlane_b32 s0, v255, 2
	v_add3_u32 v162, v162, v166, v160
	v_mfma_f32_32x32x16_bf16 v[64:79], v[240:243], v[236:239], v[64:79]
	v_add_u32_e32 v169, s0, v170
	v_add3_u32 v169, v169, v165, v160
	ds_read_b64_tr_b16 v[240:241], v162
	ds_read_b64_tr_b16 v[242:243], v169
	v_readlane_b32 s0, v255, 3
	s_nop 1
	v_add_u32_e32 v162, s0, v170
	v_readlane_b32 s0, v255, 4
	v_add3_u32 v162, v162, v166, v160
	v_mfma_f32_32x32x16_bf16 v[112:127], v[244:247], v[236:239], v[112:127]
	v_add_u32_e32 v169, s0, v170
	v_readlane_b32 s0, v255, 5
	v_add3_u32 v169, v169, v165, v160
	ds_read_b64_tr_b16 v[244:245], v162
	ds_read_b64_tr_b16 v[246:247], v169
	v_add_u32_e32 v162, s0, v170
	v_readlane_b32 s0, v255, 6
	v_add3_u32 v162, v162, v166, v160
	s_waitcnt lgkmcnt(0)
	v_mfma_f32_32x32x16_bf16 v[32:47], v[240:243], v[236:239], v[32:47]
	v_add_u32_e32 v169, s0, v170
	v_add3_u32 v169, v169, v165, v160
	ds_read_b64_tr_b16 v[240:241], v162
	ds_read_b64_tr_b16 v[242:243], v169
	v_readlane_b32 s0, v255, 7
	s_nop 1
	v_add_u32_e32 v162, s0, v170
	v_readlane_b32 s0, v255, 8
	v_add3_u32 v162, v162, v166, v160
	v_mfma_f32_32x32x16_bf16 v[48:63], v[232:235], v[236:239], v[48:63]
	v_add_u32_e32 v169, s0, v170
	v_readlane_b32 s0, v255, 9
	v_cvt_pk_bf16_f32 v232, v179, v183
	v_cvt_pk_bf16_f32 v233, v177, v180
	v_cvt_pk_bf16_f32 v234, v178, v181
	v_add3_u32 v169, v169, v165, v160
	ds_read_b64_tr_b16 v[178:179], v162
	ds_read_b64_tr_b16 v[180:181], v169
	v_add_u32_e32 v162, s0, v170
	v_readlane_b32 s0, v255, 10
	v_add3_u32 v162, v162, v166, v160
	v_mfma_f32_32x32x16_bf16 v[16:31], v[244:247], v[236:239], v[16:31]
	v_add_u32_e32 v169, s0, v170
	v_add3_u32 v169, v169, v165, v160
	v_readlane_b32 s0, v255, 11
	v_cvt_pk_bf16_f32 v235, v174, v176
	s_waitcnt lgkmcnt(0)
	v_mfma_f32_32x32x16_bf16 v[0:15], v[240:243], v[236:239], v[0:15]
	ds_read_b64_tr_b16 v[236:237], v162
	ds_read_b64_tr_b16 v[238:239], v169
	v_add_u32_e32 v162, s0, v170
	v_readlane_b32 s0, v255, 12
	v_add3_u32 v162, v162, v166, v160
	s_nop 0
	v_add_u32_e32 v169, s0, v170
	v_readlane_b32 s0, v255, 13
	v_mfma_f32_32x32x16_bf16 v[112:127], v[178:181], v[232:235], v[112:127]
	v_add3_u32 v169, v169, v165, v160
	ds_read_b64_tr_b16 v[176:177], v162
	ds_read_b64_tr_b16 v[178:179], v169
	v_add_u32_e32 v162, s0, v170
	v_readlane_b32 s0, v255, 14
	v_add3_u32 v162, v162, v166, v160
	s_nop 0
	v_add_u32_e32 v169, s0, v170
	s_waitcnt lgkmcnt(0)
	v_mfma_f32_32x32x16_bf16 v[96:111], v[236:239], v[232:235], v[96:111]
	v_add3_u32 v169, v169, v165, v160
	ds_read_b64_tr_b16 v[236:237], v162
	ds_read_b64_tr_b16 v[238:239], v169
	v_readlane_b32 s0, v255, 15
	s_nop 1
	v_add_u32_e32 v162, s0, v170
	v_readlane_b32 s0, v255, 16
	v_add3_u32 v162, v162, v166, v160
	v_mfma_f32_32x32x16_bf16 v[80:95], v[176:179], v[232:235], v[80:95]
	v_add_u32_e32 v169, s0, v170
	v_readlane_b32 s0, v255, 17
	v_add3_u32 v169, v169, v165, v160
	ds_read_b64_tr_b16 v[176:177], v162
	ds_read_b64_tr_b16 v[178:179], v169
	v_add_u32_e32 v162, s0, v170
	v_readlane_b32 s0, v255, 18
	v_add3_u32 v162, v162, v166, v160
	s_waitcnt lgkmcnt(0)
	v_mfma_f32_32x32x16_bf16 v[64:79], v[236:239], v[232:235], v[64:79]
	v_add_u32_e32 v169, s0, v170
	v_add3_u32 v169, v169, v165, v160
	ds_read_b64_tr_b16 v[236:237], v162
	ds_read_b64_tr_b16 v[238:239], v169
	v_readlane_b32 s0, v255, 19
	s_nop 1
	v_add_u32_e32 v162, s0, v170
	v_readlane_b32 s0, v255, 20
	v_add3_u32 v162, v162, v166, v160
	v_mfma_f32_32x32x16_bf16 v[48:63], v[176:179], v[232:235], v[48:63]
	v_add_u32_e32 v169, s0, v170
	v_readlane_b32 s0, v255, 21
	v_add3_u32 v169, v169, v165, v160
	ds_read_b64_tr_b16 v[176:177], v162
	ds_read_b64_tr_b16 v[178:179], v169
	v_add_u32_e32 v162, s0, v170
	v_readlane_b32 s0, v255, 22
	v_add3_u32 v162, v162, v166, v160
	s_waitcnt lgkmcnt(0)
	v_mfma_f32_32x32x16_bf16 v[32:47], v[236:239], v[232:235], v[32:47]
	v_add_u32_e32 v169, s0, v170
	v_add3_u32 v169, v169, v165, v160
	ds_read_b64_tr_b16 v[236:237], v162
	ds_read_b64_tr_b16 v[238:239], v169
	v_mfma_f32_32x32x16_bf16 v[16:31], v[176:179], v[232:235], v[16:31]
	s_waitcnt lgkmcnt(0)
	v_mfma_f32_32x32x16_bf16 v[0:15], v[236:239], v[232:235], v[0:15]
	s_waitcnt vmcnt(0)
	s_waitcnt vmcnt(0)
	s_barrier
; #define MFMA32(a, b, c) __builtin_amdgcn_mfma_f32_32x32x16_bf16((a), (b), (c), 0, 0, 0)
; DI void xattn_unit(const bf16_t* __restrict__ Qg, const bf16_t* __restrict__ Kg, const bf16_t* __restrict__ Vg, bf16_t* __restrict__ Og, lds_t* shm) {
;     ...
; #pragma unroll
;   for (int t = 0; t < 4; ++t) {
;     if (t == 1) { __builtin_amdgcn_sched_barrier(0); asm volatile("s_waitcnt vmcnt(0)" ::: "memory"); __syncthreads(); __builtin_amdgcn_sched_barrier(0); }
;     const unsigned vbase = (t == 0) ? 131072u : (unsigned)t * 32768u;
; #pragma unroll
;     for (int ks = 0; ks < 4; ++ks)
; #pragma unroll
;       for (int c = 0; c < NC; ++c) {
;         const unsigned vo = vbase + (c >> 2) * 16384 + 512 * (c & 3) + 4096 * ks;
;         const bf16x8 vf = tr_pair(shm + vo + va0, shm + vo + 2048 + va1);
;         O[c] = MFMA32(vf, P[t][ks >> 1][ks & 1], O[c]);
;       }
	v_add_u32_e32 v162, 0, v170
	v_add3_u32 v169, v162, v166, v160
	v_add3_u32 v162, v162, v165, v160
	ds_read_b64_tr_b16 v[232:233], v169 offset:32768
	ds_read_b64_tr_b16 v[234:235], v162 offset:34816
	s_add_i32 s0, 0, 0x10000
	s_add_i32 s2, s2, 1
	v_readlane_b32 s68, v254, 0
	s_nop 1
	ds_read_b64_tr_b16 v[236:237], v169 offset:33280
	ds_read_b64_tr_b16 v[238:239], v162 offset:35328
	ds_read_b64_tr_b16 v[240:241], v169 offset:33792
	ds_read_b64_tr_b16 v[242:243], v162 offset:35840
	s_waitcnt lgkmcnt(4)
	v_mfma_f32_32x32x16_bf16 v[112:127], v[232:235], v[128:131], v[112:127]
	ds_read_b64_tr_b16 v[232:233], v169 offset:34304
	ds_read_b64_tr_b16 v[234:235], v162 offset:36352
	s_waitcnt lgkmcnt(4)
	v_mfma_f32_32x32x16_bf16 v[96:111], v[236:239], v[128:131], v[96:111]
	ds_read_b64_tr_b16 v[236:237], v169 offset:49152
	ds_read_b64_tr_b16 v[238:239], v162 offset:51200
	s_waitcnt lgkmcnt(4)
	v_mfma_f32_32x32x16_bf16 v[80:95], v[240:243], v[128:131], v[80:95]
	ds_read_b64_tr_b16 v[240:241], v169 offset:49664
	ds_read_b64_tr_b16 v[242:243], v162 offset:51712
	s_waitcnt lgkmcnt(4)
	v_mfma_f32_32x32x16_bf16 v[64:79], v[232:235], v[128:131], v[64:79]
	ds_read_b64_tr_b16 v[232:233], v169 offset:50176
	ds_read_b64_tr_b16 v[234:235], v162 offset:52224
	s_waitcnt lgkmcnt(4)
	v_mfma_f32_32x32x16_bf16 v[48:63], v[236:239], v[128:131], v[48:63]
	ds_read_b64_tr_b16 v[236:237], v169 offset:50688
	ds_read_b64_tr_b16 v[238:239], v162 offset:52736
	s_waitcnt lgkmcnt(4)
	v_mfma_f32_32x32x16_bf16 v[32:47], v[240:243], v[128:131], v[32:47]
	ds_read_b64_tr_b16 v[240:241], v169 offset:36864
	ds_read_b64_tr_b16 v[242:243], v162 offset:38912
	s_waitcnt lgkmcnt(4)
	v_mfma_f32_32x32x16_bf16 v[16:31], v[232:235], v[128:131], v[16:31]
	ds_read_b64_tr_b16 v[232:233], v169 offset:37376
	ds_read_b64_tr_b16 v[234:235], v162 offset:39424
	s_waitcnt lgkmcnt(4)
	v_mfma_f32_32x32x16_bf16 v[0:15], v[236:239], v[128:131], v[0:15]
	ds_read_b64_tr_b16 v[236:237], v169 offset:37888
	ds_read_b64_tr_b16 v[238:239], v162 offset:39936
	s_waitcnt lgkmcnt(4)
	v_mfma_f32_32x32x16_bf16 v[112:127], v[240:243], v[132:135], v[112:127]
	ds_read_b64_tr_b16 v[240:241], v169 offset:38400
	ds_read_b64_tr_b16 v[242:243], v162 offset:40448
	s_waitcnt lgkmcnt(4)
	v_mfma_f32_32x32x16_bf16 v[96:111], v[232:235], v[132:135], v[96:111]
	ds_read_b64_tr_b16 v[232:233], v169 offset:53248
	ds_read_b64_tr_b16 v[234:235], v162 offset:55296
	s_waitcnt lgkmcnt(4)
	v_mfma_f32_32x32x16_bf16 v[80:95], v[236:239], v[132:135], v[80:95]
	ds_read_b64_tr_b16 v[236:237], v169 offset:53760
	ds_read_b64_tr_b16 v[238:239], v162 offset:55808
	s_waitcnt lgkmcnt(4)
	v_mfma_f32_32x32x16_bf16 v[64:79], v[240:243], v[132:135], v[64:79]
	ds_read_b64_tr_b16 v[240:241], v169 offset:54272
	ds_read_b64_tr_b16 v[242:243], v162 offset:56320
	s_waitcnt lgkmcnt(4)
	v_mfma_f32_32x32x16_bf16 v[48:63], v[232:235], v[132:135], v[48:63]
	ds_read_b64_tr_b16 v[232:233], v169 offset:54784
	ds_read_b64_tr_b16 v[234:235], v162 offset:56832
	s_waitcnt lgkmcnt(4)
	v_mfma_f32_32x32x16_bf16 v[32:47], v[236:239], v[132:135], v[32:47]
	ds_read_b64_tr_b16 v[236:237], v169 offset:40960
	ds_read_b64_tr_b16 v[238:239], v162 offset:43008
	s_waitcnt lgkmcnt(4)
	v_mfma_f32_32x32x16_bf16 v[16:31], v[240:243], v[132:135], v[16:31]
	ds_read_b64_tr_b16 v[240:241], v169 offset:41472
	ds_read_b64_tr_b16 v[242:243], v162 offset:43520
	s_waitcnt lgkmcnt(4)
	v_mfma_f32_32x32x16_bf16 v[0:15], v[232:235], v[132:135], v[0:15]
	ds_read_b64_tr_b16 v[232:233], v169 offset:41984
	ds_read_b64_tr_b16 v[234:235], v162 offset:44032
	v_cvt_pk_bf16_f32 v132, v203, v204
	v_cvt_pk_bf16_f32 v133, v205, v206
	v_cvt_pk_bf16_f32 v134, v207, v209
	v_cvt_pk_bf16_f32 v135, v211, v219
	s_waitcnt lgkmcnt(4)
	v_mfma_f32_32x32x16_bf16 v[112:127], v[236:239], v[136:139], v[112:127]
	ds_read_b64_tr_b16 v[236:237], v169 offset:42496
	ds_read_b64_tr_b16 v[238:239], v162 offset:44544
	s_waitcnt lgkmcnt(4)
	v_mfma_f32_32x32x16_bf16 v[96:111], v[240:243], v[136:139], v[96:111]
	ds_read_b64_tr_b16 v[240:241], v169 offset:57344
	ds_read_b64_tr_b16 v[242:243], v162 offset:59392
	s_waitcnt lgkmcnt(4)
	v_mfma_f32_32x32x16_bf16 v[80:95], v[232:235], v[136:139], v[80:95]
	ds_read_b64_tr_b16 v[232:233], v169 offset:57856
	ds_read_b64_tr_b16 v[234:235], v162 offset:59904
	s_waitcnt lgkmcnt(4)
	v_mfma_f32_32x32x16_bf16 v[64:79], v[236:239], v[136:139], v[64:79]
	ds_read_b64_tr_b16 v[236:237], v169 offset:58368
	ds_read_b64_tr_b16 v[238:239], v162 offset:60416
	s_waitcnt lgkmcnt(4)
	v_mfma_f32_32x32x16_bf16 v[48:63], v[240:243], v[136:139], v[48:63]
	ds_read_b64_tr_b16 v[240:241], v169 offset:58880
	ds_read_b64_tr_b16 v[242:243], v162 offset:60928
	s_waitcnt lgkmcnt(4)
	v_mfma_f32_32x32x16_bf16 v[32:47], v[232:235], v[136:139], v[32:47]
	ds_read_b64_tr_b16 v[232:233], v169 offset:45056
	ds_read_b64_tr_b16 v[234:235], v162 offset:47104
	s_waitcnt lgkmcnt(4)
	v_mfma_f32_32x32x16_bf16 v[16:31], v[236:239], v[136:139], v[16:31]
	ds_read_b64_tr_b16 v[236:237], v169 offset:45568
	ds_read_b64_tr_b16 v[238:239], v162 offset:47616
	s_waitcnt lgkmcnt(4)
	v_mfma_f32_32x32x16_bf16 v[0:15], v[240:243], v[136:139], v[0:15]
	ds_read_b64_tr_b16 v[240:241], v169 offset:46080
	ds_read_b64_tr_b16 v[242:243], v162 offset:48128
	v_cvt_pk_bf16_f32 v136, v187, v188
	v_cvt_pk_bf16_f32 v137, v189, v190
	v_cvt_pk_bf16_f32 v138, v192, v196
	v_cvt_pk_bf16_f32 v139, v200, v202
	s_waitcnt lgkmcnt(4)
	v_mfma_f32_32x32x16_bf16 v[112:127], v[232:235], v[156:159], v[112:127]
	ds_read_b64_tr_b16 v[232:233], v169 offset:46592
	ds_read_b64_tr_b16 v[234:235], v162 offset:48640
	s_waitcnt lgkmcnt(4)
; #define MFMA32(a, b, c) __builtin_amdgcn_mfma_f32_32x32x16_bf16((a), (b), (c), 0, 0, 0)
; DI void xattn_unit(const bf16_t* __restrict__ Qg, const bf16_t* __restrict__ Kg, const bf16_t* __restrict__ Vg, bf16_t* __restrict__ Og, lds_t* shm) {
;     ...
; #pragma unroll
;   for (int t = 0; t < 4; ++t) {
;     if (t == 1) { __builtin_amdgcn_sched_barrier(0); asm volatile("s_waitcnt vmcnt(0)" ::: "memory"); __syncthreads(); __builtin_amdgcn_sched_barrier(0); }
;     const unsigned vbase = (t == 0) ? 131072u : (unsigned)t * 32768u;
; #pragma unroll
;     for (int ks = 0; ks < 4; ++ks)
; #pragma unroll
;       for (int c = 0; c < NC; ++c) {
;         const unsigned vo = vbase + (c >> 2) * 16384 + 512 * (c & 3) + 4096 * ks;
;         const bf16x8 vf = tr_pair(shm + vo + va0, shm + vo + 2048 + va1);
;         O[c] = MFMA32(vf, P[t][ks >> 1][ks & 1], O[c]);
;       }
	v_mfma_f32_32x32x16_bf16 v[96:111], v[236:239], v[156:159], v[96:111]
	ds_read_b64_tr_b16 v[236:237], v169 offset:61440
	ds_read_b64_tr_b16 v[238:239], v162 offset:63488
	s_waitcnt lgkmcnt(4)
	v_mfma_f32_32x32x16_bf16 v[80:95], v[240:243], v[156:159], v[80:95]
	ds_read_b64_tr_b16 v[240:241], v169 offset:61952
	ds_read_b64_tr_b16 v[242:243], v162 offset:64000
	s_waitcnt lgkmcnt(4)
	v_mfma_f32_32x32x16_bf16 v[64:79], v[232:235], v[156:159], v[64:79]
	ds_read_b64_tr_b16 v[232:233], v169 offset:62464
	ds_read_b64_tr_b16 v[234:235], v162 offset:64512
	s_waitcnt lgkmcnt(4)
	v_mfma_f32_32x32x16_bf16 v[48:63], v[236:239], v[156:159], v[48:63]
	ds_read_b64_tr_b16 v[236:237], v169 offset:62976
	ds_read_b64_tr_b16 v[238:239], v162 offset:65024
	s_waitcnt lgkmcnt(4)
	v_mfma_f32_32x32x16_bf16 v[32:47], v[240:243], v[156:159], v[32:47]
	v_add_u32_e32 v240, s0, v170
	v_readlane_b32 s0, v255, 23
	s_nop 1
	v_add3_u32 v240, v240, v166, v160
	s_nop 0
	v_add_u32_e32 v241, s0, v170
	v_add3_u32 v242, v241, v165, v160
	ds_read_b64_tr_b16 v[240:241], v240
	ds_read_b64_tr_b16 v[242:243], v242
	s_add_i32 s0, 0, 0x10200
	s_waitcnt lgkmcnt(4)
	v_mfma_f32_32x32x16_bf16 v[16:31], v[232:235], v[156:159], v[16:31]
	v_add_u32_e32 v232, s0, v170
	v_readlane_b32 s0, v255, 24
	s_nop 1
	v_add3_u32 v232, v232, v166, v160
	s_nop 0
	v_add_u32_e32 v233, s0, v170
	v_add3_u32 v234, v233, v165, v160
	ds_read_b64_tr_b16 v[232:233], v232
	ds_read_b64_tr_b16 v[234:235], v234
	s_add_i32 s0, 0, 0x10400
	s_waitcnt lgkmcnt(4)
	v_mfma_f32_32x32x16_bf16 v[0:15], v[236:239], v[156:159], v[0:15]
	v_add_u32_e32 v236, s0, v170
	v_readlane_b32 s0, v255, 25
	s_nop 1
	v_add3_u32 v236, v236, v166, v160
	s_nop 0
	v_add_u32_e32 v237, s0, v170
	v_add3_u32 v238, v237, v165, v160
	ds_read_b64_tr_b16 v[236:237], v236
	ds_read_b64_tr_b16 v[238:239], v238
	s_add_i32 s0, 0, 0x10600
	s_waitcnt lgkmcnt(4)
	v_mfma_f32_32x32x16_bf16 v[112:127], v[240:243], v[152:155], v[112:127]
	v_add_u32_e32 v240, s0, v170
	v_readlane_b32 s0, v255, 26
	s_nop 1
	v_add3_u32 v240, v240, v166, v160
	s_nop 0
	v_add_u32_e32 v241, s0, v170
	v_add3_u32 v242, v241, v165, v160
	ds_read_b64_tr_b16 v[240:241], v240
	ds_read_b64_tr_b16 v[242:243], v242
	s_add_i32 s0, 0, 0x14000
	s_waitcnt lgkmcnt(4)
	v_mfma_f32_32x32x16_bf16 v[96:111], v[232:235], v[152:155], v[96:111]
	v_add_u32_e32 v232, s0, v170
	v_readlane_b32 s0, v255, 27
	s_nop 1
	v_add3_u32 v232, v232, v166, v160
	s_nop 0
	v_add_u32_e32 v233, s0, v170
	v_add3_u32 v234, v233, v165, v160
	ds_read_b64_tr_b16 v[232:233], v232
	ds_read_b64_tr_b16 v[234:235], v234
	s_add_i32 s0, 0, 0x14200
	s_waitcnt lgkmcnt(4)
	v_mfma_f32_32x32x16_bf16 v[80:95], v[236:239], v[152:155], v[80:95]
	v_add_u32_e32 v236, s0, v170
	v_readlane_b32 s0, v255, 28
	s_nop 1
	v_add3_u32 v236, v236, v166, v160
	s_nop 0
	v_add_u32_e32 v237, s0, v170
	v_add3_u32 v238, v237, v165, v160
	ds_read_b64_tr_b16 v[236:237], v236
	ds_read_b64_tr_b16 v[238:239], v238
	s_add_i32 s0, 0, 0x14400
	s_waitcnt lgkmcnt(4)
	v_mfma_f32_32x32x16_bf16 v[64:79], v[240:243], v[152:155], v[64:79]
	v_add_u32_e32 v240, s0, v170
	v_readlane_b32 s0, v255, 29
	s_nop 1
	v_add3_u32 v240, v240, v166, v160
	s_nop 0
	v_add_u32_e32 v241, s0, v170
	v_add3_u32 v242, v241, v165, v160
	ds_read_b64_tr_b16 v[240:241], v240
	ds_read_b64_tr_b16 v[242:243], v242
	s_add_i32 s0, 0, 0x14600
	s_waitcnt lgkmcnt(4)
	v_mfma_f32_32x32x16_bf16 v[48:63], v[232:235], v[152:155], v[48:63]
	v_add_u32_e32 v232, s0, v170
	v_readlane_b32 s0, v255, 30
	s_nop 1
	v_add3_u32 v232, v232, v166, v160
	s_nop 0
	v_add_u32_e32 v233, s0, v170
	v_add3_u32 v234, v233, v165, v160
	ds_read_b64_tr_b16 v[232:233], v232
	ds_read_b64_tr_b16 v[234:235], v234
	v_readlane_b32 s0, v255, 31
	s_nop 1
	s_waitcnt lgkmcnt(4)
	v_mfma_f32_32x32x16_bf16 v[32:47], v[236:239], v[152:155], v[32:47]
	v_add_u32_e32 v236, s0, v170
	v_readlane_b32 s0, v255, 32
	s_nop 1
	v_add3_u32 v236, v236, v166, v160
	s_nop 0
	v_add_u32_e32 v237, s0, v170
	v_add3_u32 v238, v237, v165, v160
	ds_read_b64_tr_b16 v[236:237], v236
	ds_read_b64_tr_b16 v[238:239], v238
	v_readlane_b32 s0, v255, 33
	s_nop 1
	s_waitcnt lgkmcnt(4)
	v_mfma_f32_32x32x16_bf16 v[16:31], v[240:243], v[152:155], v[16:31]
	v_add_u32_e32 v240, s0, v170
	v_readlane_b32 s0, v255, 34
	s_nop 1
	v_add3_u32 v240, v240, v166, v160
	s_nop 0
	v_add_u32_e32 v241, s0, v170
	v_add3_u32 v242, v241, v165, v160
	ds_read_b64_tr_b16 v[240:241], v240
	ds_read_b64_tr_b16 v[242:243], v242
	v_readlane_b32 s0, v255, 35
	s_nop 1
	s_waitcnt lgkmcnt(4)
	v_mfma_f32_32x32x16_bf16 v[0:15], v[232:235], v[152:155], v[0:15]
	v_add_u32_e32 v232, s0, v170
	v_readlane_b32 s0, v255, 36
	s_nop 1
	v_add3_u32 v232, v232, v166, v160
	s_nop 0
	v_add_u32_e32 v233, s0, v170
	v_add3_u32 v234, v233, v165, v160
	ds_read_b64_tr_b16 v[232:233], v232
	ds_read_b64_tr_b16 v[234:235], v234
	v_readlane_b32 s0, v255, 37
	s_nop 1
	s_waitcnt lgkmcnt(4)
	v_mfma_f32_32x32x16_bf16 v[112:127], v[236:239], v[148:151], v[112:127]
	v_add_u32_e32 v236, s0, v170
	v_readlane_b32 s0, v255, 38
	s_nop 1
	v_add3_u32 v236, v236, v166, v160
	s_nop 0
	v_add_u32_e32 v237, s0, v170
	v_add3_u32 v238, v237, v165, v160
	ds_read_b64_tr_b16 v[236:237], v236
	ds_read_b64_tr_b16 v[238:239], v238
	v_readlane_b32 s0, v255, 39
	s_nop 1
	s_waitcnt lgkmcnt(4)
	v_mfma_f32_32x32x16_bf16 v[96:111], v[240:243], v[148:151], v[96:111]
	v_add_u32_e32 v240, s0, v170
	v_readlane_b32 s0, v255, 40
	s_nop 1
	v_add3_u32 v240, v240, v166, v160
	s_nop 0
	v_add_u32_e32 v241, s0, v170
	v_add3_u32 v242, v241, v165, v160
	ds_read_b64_tr_b16 v[240:241], v240
	ds_read_b64_tr_b16 v[242:243], v242
	v_readlane_b32 s0, v255, 41
	s_nop 1
	s_waitcnt lgkmcnt(4)
; #define MFMA32(a, b, c) __builtin_amdgcn_mfma_f32_32x32x16_bf16((a), (b), (c), 0, 0, 0)
; DI void xattn_unit(const bf16_t* __restrict__ Qg, const bf16_t* __restrict__ Kg, const bf16_t* __restrict__ Vg, bf16_t* __restrict__ Og, lds_t* shm) {
;     ...
; #pragma unroll
;   for (int t = 0; t < 4; ++t) {
;     if (t == 1) { __builtin_amdgcn_sched_barrier(0); asm volatile("s_waitcnt vmcnt(0)" ::: "memory"); __syncthreads(); __builtin_amdgcn_sched_barrier(0); }
;     const unsigned vbase = (t == 0) ? 131072u : (unsigned)t * 32768u;
; #pragma unroll
;     for (int ks = 0; ks < 4; ++ks)
; #pragma unroll
;       for (int c = 0; c < NC; ++c) {
;         const unsigned vo = vbase + (c >> 2) * 16384 + 512 * (c & 3) + 4096 * ks;
;         const bf16x8 vf = tr_pair(shm + vo + va0, shm + vo + 2048 + va1);
;         O[c] = MFMA32(vf, P[t][ks >> 1][ks & 1], O[c]);
;       }
	v_mfma_f32_32x32x16_bf16 v[80:95], v[232:235], v[148:151], v[80:95]
	v_add_u32_e32 v232, s0, v170
	v_readlane_b32 s0, v255, 42
	s_nop 1
	v_add3_u32 v232, v232, v166, v160
	s_nop 0
	v_add_u32_e32 v233, s0, v170
	v_add3_u32 v234, v233, v165, v160
	ds_read_b64_tr_b16 v[232:233], v232
	ds_read_b64_tr_b16 v[234:235], v234
	v_readlane_b32 s0, v255, 43
	s_nop 1
	s_waitcnt lgkmcnt(4)
	v_mfma_f32_32x32x16_bf16 v[64:79], v[236:239], v[148:151], v[64:79]
	v_add_u32_e32 v236, s0, v170
	v_readlane_b32 s0, v255, 44
	s_nop 1
	v_add3_u32 v236, v236, v166, v160
	s_nop 0
	v_add_u32_e32 v237, s0, v170
	v_add3_u32 v238, v237, v165, v160
	ds_read_b64_tr_b16 v[236:237], v236
	ds_read_b64_tr_b16 v[238:239], v238
	v_readlane_b32 s0, v255, 45
	s_nop 1
	s_waitcnt lgkmcnt(4)
	v_mfma_f32_32x32x16_bf16 v[48:63], v[240:243], v[148:151], v[48:63]
	v_add_u32_e32 v240, s0, v170
	v_readlane_b32 s0, v255, 46
	s_nop 1
	v_add3_u32 v240, v240, v166, v160
	s_nop 0
	v_add_u32_e32 v241, s0, v170
	v_add3_u32 v242, v241, v165, v160
	ds_read_b64_tr_b16 v[240:241], v240
	ds_read_b64_tr_b16 v[242:243], v242
	s_add_i32 s0, 0, 0x12000
	s_waitcnt lgkmcnt(4)
	v_mfma_f32_32x32x16_bf16 v[32:47], v[232:235], v[148:151], v[32:47]
	v_add_u32_e32 v232, s0, v170
	v_readlane_b32 s0, v255, 47
	s_nop 1
	v_add3_u32 v232, v232, v166, v160
	s_nop 0
	v_add_u32_e32 v233, s0, v170
	v_add3_u32 v234, v233, v165, v160
	ds_read_b64_tr_b16 v[232:233], v232
	ds_read_b64_tr_b16 v[234:235], v234
	s_add_i32 s0, 0, 0x12200
	s_waitcnt lgkmcnt(4)
	v_mfma_f32_32x32x16_bf16 v[16:31], v[236:239], v[148:151], v[16:31]
	v_add_u32_e32 v236, s0, v170
	v_readlane_b32 s0, v255, 48
	s_nop 1
	v_add3_u32 v236, v236, v166, v160
	s_nop 0
	v_add_u32_e32 v237, s0, v170
	v_add3_u32 v238, v237, v165, v160
	ds_read_b64_tr_b16 v[236:237], v236
	ds_read_b64_tr_b16 v[238:239], v238
	s_add_i32 s0, 0, 0x12400
	s_waitcnt lgkmcnt(4)
	v_mfma_f32_32x32x16_bf16 v[0:15], v[240:243], v[148:151], v[0:15]
	v_add_u32_e32 v240, s0, v170
	v_readlane_b32 s0, v255, 49
	s_nop 1
	v_add3_u32 v240, v240, v166, v160
	s_nop 0
	v_add_u32_e32 v241, s0, v170
	v_add3_u32 v242, v241, v165, v160
	ds_read_b64_tr_b16 v[240:241], v240
	ds_read_b64_tr_b16 v[242:243], v242
	s_add_i32 s0, 0, 0x12600
	s_waitcnt lgkmcnt(4)
	v_mfma_f32_32x32x16_bf16 v[112:127], v[232:235], v[140:143], v[112:127]
	v_add_u32_e32 v232, s0, v170
	v_readlane_b32 s0, v255, 50
	s_nop 1
	v_add3_u32 v232, v232, v166, v160
	s_nop 0
	v_add_u32_e32 v233, s0, v170
	v_add3_u32 v234, v233, v165, v160
	ds_read_b64_tr_b16 v[232:233], v232
	ds_read_b64_tr_b16 v[234:235], v234
	s_add_i32 s0, 0, 0x16000
	s_waitcnt lgkmcnt(4)
	v_mfma_f32_32x32x16_bf16 v[96:111], v[236:239], v[140:143], v[96:111]
	v_add_u32_e32 v236, s0, v170
	v_readlane_b32 s0, v255, 51
	s_nop 1
	v_add3_u32 v236, v236, v166, v160
	s_nop 0
	v_add_u32_e32 v237, s0, v170
	v_add3_u32 v238, v237, v165, v160
	ds_read_b64_tr_b16 v[236:237], v236
	ds_read_b64_tr_b16 v[238:239], v238
	s_add_i32 s0, 0, 0x16200
	s_waitcnt lgkmcnt(4)
	v_mfma_f32_32x32x16_bf16 v[80:95], v[240:243], v[140:143], v[80:95]
	v_add_u32_e32 v240, s0, v170
	v_readlane_b32 s0, v255, 52
	s_nop 1
	v_add3_u32 v240, v240, v166, v160
	s_nop 0
	v_add_u32_e32 v241, s0, v170
	v_add3_u32 v242, v241, v165, v160
	ds_read_b64_tr_b16 v[240:241], v240
	ds_read_b64_tr_b16 v[242:243], v242
	s_add_i32 s0, 0, 0x16400
	s_waitcnt lgkmcnt(4)
	v_mfma_f32_32x32x16_bf16 v[64:79], v[232:235], v[140:143], v[64:79]
	v_add_u32_e32 v232, s0, v170
	v_readlane_b32 s0, v255, 53
	s_nop 1
	v_add3_u32 v232, v232, v166, v160
	s_nop 0
	v_add_u32_e32 v233, s0, v170
	v_add3_u32 v234, v233, v165, v160
	ds_read_b64_tr_b16 v[232:233], v232
	ds_read_b64_tr_b16 v[234:235], v234
	s_add_i32 s0, 0, 0x16600
	s_waitcnt lgkmcnt(4)
	v_mfma_f32_32x32x16_bf16 v[48:63], v[236:239], v[140:143], v[48:63]
	v_add_u32_e32 v236, s0, v170
	v_readlane_b32 s0, v255, 54
	s_nop 1
	v_add3_u32 v236, v236, v166, v160
	s_nop 0
	v_add_u32_e32 v237, s0, v170
	v_add3_u32 v238, v237, v165, v160
	ds_read_b64_tr_b16 v[236:237], v236
	ds_read_b64_tr_b16 v[238:239], v238
	v_readlane_b32 s0, v255, 55
	s_nop 1
	s_waitcnt lgkmcnt(4)
	v_mfma_f32_32x32x16_bf16 v[32:47], v[240:243], v[140:143], v[32:47]
	v_add_u32_e32 v240, s0, v170
	v_readlane_b32 s0, v255, 56
	s_nop 1
	v_add3_u32 v240, v240, v166, v160
	v_add_u32_e32 v241, s0, v170
	v_add3_u32 v242, v241, v165, v160
	ds_read_b64_tr_b16 v[240:241], v240
	ds_read_b64_tr_b16 v[242:243], v242
	v_readlane_b32 s0, v255, 57
	s_nop 1
	s_waitcnt lgkmcnt(4)
	v_mfma_f32_32x32x16_bf16 v[16:31], v[232:235], v[140:143], v[16:31]
	v_add_u32_e32 v232, s0, v170
	v_readlane_b32 s0, v255, 58
	s_nop 1
	v_add3_u32 v232, v232, v166, v160
	v_add_u32_e32 v233, s0, v170
	v_add3_u32 v234, v233, v165, v160
	ds_read_b64_tr_b16 v[232:233], v232
	ds_read_b64_tr_b16 v[234:235], v234
	v_readlane_b32 s0, v255, 59
	s_nop 1
	s_waitcnt lgkmcnt(4)
	v_mfma_f32_32x32x16_bf16 v[0:15], v[236:239], v[140:143], v[0:15]
	v_add_u32_e32 v236, s0, v170
	v_readlane_b32 s0, v255, 60
	s_nop 1
	v_add3_u32 v236, v236, v166, v160
	v_add_u32_e32 v237, s0, v170
	v_add3_u32 v238, v237, v165, v160
	ds_read_b64_tr_b16 v[236:237], v236
	ds_read_b64_tr_b16 v[238:239], v238
	v_readlane_b32 s0, v255, 61
	s_nop 1
	v_cvt_pk_bf16_f32 v140, v171, v172
	s_waitcnt lgkmcnt(4)
	v_mfma_f32_32x32x16_bf16 v[112:127], v[240:243], v[144:147], v[112:127]
	v_add_u32_e32 v240, s0, v170
	v_readlane_b32 s0, v255, 62
	s_nop 1
	v_add3_u32 v240, v240, v166, v160
	v_add_u32_e32 v241, s0, v170
	v_add3_u32 v242, v241, v165, v160
	ds_read_b64_tr_b16 v[240:241], v240
	ds_read_b64_tr_b16 v[242:243], v242
	v_cvt_pk_bf16_f32 v141, v173, v175
	s_waitcnt lgkmcnt(4)
; #define MFMA32(a, b, c) __builtin_amdgcn_mfma_f32_32x32x16_bf16((a), (b), (c), 0, 0, 0)
; DI void xattn_unit(const bf16_t* __restrict__ Qg, const bf16_t* __restrict__ Kg, const bf16_t* __restrict__ Vg, bf16_t* __restrict__ Og, lds_t* shm) {
;     ...
; #pragma unroll
;   for (int t = 0; t < 4; ++t) {
;     if (t == 1) { __builtin_amdgcn_sched_barrier(0); asm volatile("s_waitcnt vmcnt(0)" ::: "memory"); __syncthreads(); __builtin_amdgcn_sched_barrier(0); }
;     const unsigned vbase = (t == 0) ? 131072u : (unsigned)t * 32768u;
; #pragma unroll
;     for (int ks = 0; ks < 4; ++ks)
; #pragma unroll
;       for (int c = 0; c < NC; ++c) {
;         const unsigned vo = vbase + (c >> 2) * 16384 + 512 * (c & 3) + 4096 * ks;
;         const bf16x8 vf = tr_pair(shm + vo + va0, shm + vo + 2048 + va1);
;         O[c] = MFMA32(vf, P[t][ks >> 1][ks & 1], O[c]);
;       }
	v_mfma_f32_32x32x16_bf16 v[96:111], v[232:235], v[144:147], v[96:111]
	v_add_u32_e32 v232, s83, v170
	v_add_u32_e32 v233, s84, v170
	v_add3_u32 v232, v232, v166, v160
	v_add3_u32 v234, v233, v165, v160
	ds_read_b64_tr_b16 v[232:233], v232
	ds_read_b64_tr_b16 v[234:235], v234
	s_add_i32 s0, 0, 0x18000
	v_cvt_pk_bf16_f32 v142, v182, v184
	s_waitcnt lgkmcnt(4)
	v_mfma_f32_32x32x16_bf16 v[80:95], v[236:239], v[144:147], v[80:95]
	v_add_u32_e32 v236, s85, v170
	v_add_u32_e32 v237, s86, v170
	v_add3_u32 v236, v236, v166, v160
	v_add3_u32 v238, v237, v165, v160
	ds_read_b64_tr_b16 v[236:237], v236
	ds_read_b64_tr_b16 v[238:239], v238
	v_cvt_pk_bf16_f32 v143, v185, v186
	s_waitcnt lgkmcnt(4)
	v_mfma_f32_32x32x16_bf16 v[64:79], v[240:243], v[144:147], v[64:79]
	v_add_u32_e32 v240, s87, v170
	v_add_u32_e32 v241, s88, v170
	v_add3_u32 v240, v240, v166, v160
	v_add3_u32 v242, v241, v165, v160
	ds_read_b64_tr_b16 v[240:241], v240
	ds_read_b64_tr_b16 v[242:243], v242
	s_waitcnt lgkmcnt(4)
	v_mfma_f32_32x32x16_bf16 v[48:63], v[232:235], v[144:147], v[48:63]
	v_add_u32_e32 v232, s89, v170
	v_add_u32_e32 v233, s90, v170
	v_add3_u32 v232, v232, v166, v160
	v_add3_u32 v234, v233, v165, v160
	ds_read_b64_tr_b16 v[232:233], v232
	ds_read_b64_tr_b16 v[234:235], v234
	s_waitcnt lgkmcnt(4)
	v_mfma_f32_32x32x16_bf16 v[32:47], v[236:239], v[144:147], v[32:47]
	v_add_u32_e32 v236, s0, v170
	v_add_u32_e32 v237, s91, v170
	v_add3_u32 v236, v236, v166, v160
	v_add3_u32 v238, v237, v165, v160
	ds_read_b64_tr_b16 v[236:237], v236
	ds_read_b64_tr_b16 v[238:239], v238
	s_add_i32 s0, 0, 0x18200
	s_waitcnt lgkmcnt(4)
	v_mfma_f32_32x32x16_bf16 v[16:31], v[240:243], v[144:147], v[16:31]
	v_add_u32_e32 v240, s0, v170
	v_add_u32_e32 v241, s92, v170
	v_add3_u32 v240, v240, v166, v160
	v_add3_u32 v242, v241, v165, v160
	ds_read_b64_tr_b16 v[240:241], v240
	ds_read_b64_tr_b16 v[242:243], v242
	s_add_i32 s0, 0, 0x18400
	s_waitcnt lgkmcnt(4)
	v_mfma_f32_32x32x16_bf16 v[0:15], v[232:235], v[144:147], v[0:15]
	v_add_u32_e32 v232, s0, v170
	v_add_u32_e32 v233, s93, v170
	v_add3_u32 v232, v232, v166, v160
	v_add3_u32 v234, v233, v165, v160
	ds_read_b64_tr_b16 v[232:233], v232
	ds_read_b64_tr_b16 v[234:235], v234
	s_add_i32 s0, 0, 0x18600
	v_cvt_pk_bf16_f32 v128, v222, v223
	s_waitcnt lgkmcnt(4)
	v_mfma_f32_32x32x16_bf16 v[112:127], v[236:239], v[140:143], v[112:127]
	v_add_u32_e32 v236, s0, v170
	v_add_u32_e32 v237, s94, v170
	v_add3_u32 v236, v236, v166, v160
	v_add3_u32 v238, v237, v165, v160
	ds_read_b64_tr_b16 v[236:237], v236
	ds_read_b64_tr_b16 v[238:239], v238
	s_add_i32 s0, 0, 0x1c000
	v_cvt_pk_bf16_f32 v129, v224, v225
	s_waitcnt lgkmcnt(4)
	v_mfma_f32_32x32x16_bf16 v[96:111], v[240:243], v[140:143], v[96:111]
	v_add_u32_e32 v240, s0, v170
	v_add_u32_e32 v241, s95, v170
	v_add3_u32 v240, v240, v166, v160
	v_add3_u32 v242, v241, v165, v160
	ds_read_b64_tr_b16 v[240:241], v240
	ds_read_b64_tr_b16 v[242:243], v242
	s_add_i32 s0, 0, 0x1c200
	v_cvt_pk_bf16_f32 v130, v226, v228
	s_waitcnt lgkmcnt(4)
	v_mfma_f32_32x32x16_bf16 v[80:95], v[232:235], v[140:143], v[80:95]
	v_add_u32_e32 v232, s0, v170
	v_add_u32_e32 v233, s96, v170
	v_add3_u32 v232, v232, v166, v160
	v_add3_u32 v234, v233, v165, v160
	ds_read_b64_tr_b16 v[232:233], v232
	ds_read_b64_tr_b16 v[234:235], v234
	s_add_i32 s0, 0, 0x1c400
	v_cvt_pk_bf16_f32 v131, v229, v230
	s_waitcnt lgkmcnt(4)
	v_mfma_f32_32x32x16_bf16 v[64:79], v[236:239], v[140:143], v[64:79]
	v_add_u32_e32 v236, s0, v170
	v_add_u32_e32 v237, s97, v170
	v_add3_u32 v236, v236, v166, v160
	v_add3_u32 v238, v237, v165, v160
	ds_read_b64_tr_b16 v[236:237], v236
	ds_read_b64_tr_b16 v[238:239], v238
	s_add_i32 s0, 0, 0x1c600
	s_waitcnt lgkmcnt(4)
	v_mfma_f32_32x32x16_bf16 v[48:63], v[240:243], v[140:143], v[48:63]
	v_add_u32_e32 v240, s0, v170
	v_add_u32_e32 v241, s8, v170
	v_add3_u32 v240, v240, v166, v160
	v_add3_u32 v242, v241, v165, v160
	ds_read_b64_tr_b16 v[240:241], v240
	ds_read_b64_tr_b16 v[242:243], v242
	s_add_i32 s0, 0, 0x1a000
	s_waitcnt lgkmcnt(4)
	v_mfma_f32_32x32x16_bf16 v[32:47], v[232:235], v[140:143], v[32:47]
	v_add_u32_e32 v232, s9, v170
	v_add_u32_e32 v233, s10, v170
	v_add3_u32 v232, v232, v166, v160
	v_add3_u32 v234, v233, v165, v160
	ds_read_b64_tr_b16 v[232:233], v232
	ds_read_b64_tr_b16 v[234:235], v234
	s_waitcnt lgkmcnt(4)
	v_mfma_f32_32x32x16_bf16 v[16:31], v[236:239], v[140:143], v[16:31]
	v_add_u32_e32 v236, s11, v170
	v_add_u32_e32 v237, s18, v170
	v_add3_u32 v236, v236, v166, v160
	v_add3_u32 v238, v237, v165, v160
	ds_read_b64_tr_b16 v[236:237], v236
	ds_read_b64_tr_b16 v[238:239], v238
	s_waitcnt lgkmcnt(4)
	v_mfma_f32_32x32x16_bf16 v[0:15], v[240:243], v[140:143], v[0:15]
	v_add_u32_e32 v240, s19, v170
	v_add_u32_e32 v241, s34, v170
	v_add3_u32 v240, v240, v166, v160
	v_add3_u32 v242, v241, v165, v160
	ds_read_b64_tr_b16 v[240:241], v240
	ds_read_b64_tr_b16 v[242:243], v242
	s_waitcnt lgkmcnt(4)
	v_mfma_f32_32x32x16_bf16 v[112:127], v[232:235], v[136:139], v[112:127]
	v_add_u32_e32 v232, s20, v170
	v_add_u32_e32 v233, s21, v170
	v_add3_u32 v232, v232, v166, v160
	v_add3_u32 v234, v233, v165, v160
	ds_read_b64_tr_b16 v[232:233], v232
	ds_read_b64_tr_b16 v[234:235], v234
	s_waitcnt lgkmcnt(4)
	v_mfma_f32_32x32x16_bf16 v[96:111], v[236:239], v[136:139], v[96:111]
	v_add_u32_e32 v236, s22, v170
	v_add_u32_e32 v237, s23, v170
	v_add3_u32 v236, v236, v166, v160
	v_add3_u32 v238, v237, v165, v160
	ds_read_b64_tr_b16 v[236:237], v236
	ds_read_b64_tr_b16 v[238:239], v238
	s_waitcnt lgkmcnt(4)
; #define MFMA32(a, b, c) __builtin_amdgcn_mfma_f32_32x32x16_bf16((a), (b), (c), 0, 0, 0)
; DI void xattn_unit(const bf16_t* __restrict__ Qg, const bf16_t* __restrict__ Kg, const bf16_t* __restrict__ Vg, bf16_t* __restrict__ Og, lds_t* shm) {
;     ...
; #pragma unroll
;   for (int t = 0; t < 4; ++t) {
;     if (t == 1) { __builtin_amdgcn_sched_barrier(0); asm volatile("s_waitcnt vmcnt(0)" ::: "memory"); __syncthreads(); __builtin_amdgcn_sched_barrier(0); }
;     const unsigned vbase = (t == 0) ? 131072u : (unsigned)t * 32768u;
; #pragma unroll
;     for (int ks = 0; ks < 4; ++ks)
; #pragma unroll
;       for (int c = 0; c < NC; ++c) {
;         const unsigned vo = vbase + (c >> 2) * 16384 + 512 * (c & 3) + 4096 * ks;
;         const bf16x8 vf = tr_pair(shm + vo + va0, shm + vo + 2048 + va1);
;         O[c] = MFMA32(vf, P[t][ks >> 1][ks & 1], O[c]);
;       }
	v_mfma_f32_32x32x16_bf16 v[80:95], v[240:243], v[136:139], v[80:95]
	v_add_u32_e32 v240, s3, v170
	v_add_u32_e32 v241, s15, v170
	v_add3_u32 v240, v240, v166, v160
	v_add3_u32 v242, v241, v165, v160
	ds_read_b64_tr_b16 v[240:241], v240
	ds_read_b64_tr_b16 v[242:243], v242
	s_waitcnt lgkmcnt(4)
	v_mfma_f32_32x32x16_bf16 v[64:79], v[232:235], v[136:139], v[64:79]
	v_add_u32_e32 v232, s35, v170
	v_add_u32_e32 v233, s40, v170
	v_add3_u32 v232, v232, v166, v160
	v_add3_u32 v234, v233, v165, v160
	ds_read_b64_tr_b16 v[232:233], v232
	ds_read_b64_tr_b16 v[234:235], v234
	s_waitcnt lgkmcnt(4)
	v_mfma_f32_32x32x16_bf16 v[48:63], v[236:239], v[136:139], v[48:63]
	v_add_u32_e32 v236, s41, v170
	v_add_u32_e32 v237, s42, v170
	v_add3_u32 v236, v236, v166, v160
	v_add3_u32 v238, v237, v165, v160
	ds_read_b64_tr_b16 v[236:237], v236
	ds_read_b64_tr_b16 v[238:239], v238
	s_waitcnt lgkmcnt(4)
	v_mfma_f32_32x32x16_bf16 v[32:47], v[240:243], v[136:139], v[32:47]
	v_add_u32_e32 v240, s0, v170
	v_add_u32_e32 v241, s43, v170
	v_add3_u32 v240, v240, v166, v160
	v_add3_u32 v242, v241, v165, v160
	ds_read_b64_tr_b16 v[240:241], v240
	ds_read_b64_tr_b16 v[242:243], v242
	s_add_i32 s0, 0, 0x1a200
	s_waitcnt lgkmcnt(4)
	v_mfma_f32_32x32x16_bf16 v[16:31], v[232:235], v[136:139], v[16:31]
	v_add_u32_e32 v232, s0, v170
	v_add_u32_e32 v233, s46, v170
	v_add3_u32 v232, v232, v166, v160
	v_add3_u32 v234, v233, v165, v160
	ds_read_b64_tr_b16 v[232:233], v232
	ds_read_b64_tr_b16 v[234:235], v234
	s_add_i32 s0, 0, 0x1a400
	s_waitcnt lgkmcnt(4)
	v_mfma_f32_32x32x16_bf16 v[0:15], v[236:239], v[136:139], v[0:15]
	v_add_u32_e32 v236, s0, v170
	v_add_u32_e32 v237, s47, v170
	v_add3_u32 v236, v236, v166, v160
	v_add3_u32 v238, v237, v165, v160
	ds_read_b64_tr_b16 v[236:237], v236
	ds_read_b64_tr_b16 v[238:239], v238
	s_add_i32 s0, 0, 0x1a600
	s_waitcnt lgkmcnt(4)
	v_mfma_f32_32x32x16_bf16 v[112:127], v[240:243], v[132:135], v[112:127]
	v_add_u32_e32 v240, s0, v170
	v_add_u32_e32 v241, s48, v170
	v_add3_u32 v240, v240, v166, v160
	v_add3_u32 v242, v241, v165, v160
	ds_read_b64_tr_b16 v[240:241], v240
	ds_read_b64_tr_b16 v[242:243], v242
	s_add_i32 s0, 0, 0x1e000
	s_waitcnt lgkmcnt(4)
	v_mfma_f32_32x32x16_bf16 v[96:111], v[232:235], v[132:135], v[96:111]
	v_add_u32_e32 v232, s0, v170
	v_add_u32_e32 v233, s49, v170
	v_add3_u32 v232, v232, v166, v160
	v_add3_u32 v234, v233, v165, v160
	ds_read_b64_tr_b16 v[232:233], v232
	ds_read_b64_tr_b16 v[234:235], v234
	s_add_i32 s0, 0, 0x1e200
	s_waitcnt lgkmcnt(4)
	v_mfma_f32_32x32x16_bf16 v[80:95], v[236:239], v[132:135], v[80:95]
	v_add_u32_e32 v236, s0, v170
	v_add_u32_e32 v237, s52, v170
	v_add3_u32 v236, v236, v166, v160
	v_add3_u32 v238, v237, v165, v160
	ds_read_b64_tr_b16 v[236:237], v236
	ds_read_b64_tr_b16 v[238:239], v238
	s_add_i32 s0, 0, 0x1e400
	s_waitcnt lgkmcnt(4)
	v_mfma_f32_32x32x16_bf16 v[64:79], v[240:243], v[132:135], v[64:79]
	v_add_u32_e32 v240, s0, v170
	v_add_u32_e32 v241, s53, v170
	v_add3_u32 v240, v240, v166, v160
	v_add3_u32 v242, v241, v165, v160
	ds_read_b64_tr_b16 v[240:241], v240
	ds_read_b64_tr_b16 v[242:243], v242
	s_add_i32 s0, 0, 0x1e600
	s_waitcnt lgkmcnt(4)
	v_mfma_f32_32x32x16_bf16 v[48:63], v[232:235], v[132:135], v[48:63]
	v_add_u32_e32 v232, s0, v170
	v_add_u32_e32 v233, s54, v170
	v_add3_u32 v232, v232, v166, v160
	v_add3_u32 v234, v233, v165, v160
	ds_read_b64_tr_b16 v[232:233], v232
	ds_read_b64_tr_b16 v[234:235], v234
	s_waitcnt lgkmcnt(4)
	v_mfma_f32_32x32x16_bf16 v[32:47], v[236:239], v[132:135], v[32:47]
	v_add_u32_e32 v236, s55, v170
	v_add_u32_e32 v237, s56, v170
	v_add3_u32 v236, v236, v166, v160
	v_add3_u32 v238, v237, v165, v160
	ds_read_b64_tr_b16 v[236:237], v236
	ds_read_b64_tr_b16 v[238:239], v238
	s_waitcnt lgkmcnt(4)
	v_mfma_f32_32x32x16_bf16 v[16:31], v[240:243], v[132:135], v[16:31]
	v_add_u32_e32 v240, s57, v170
	v_add_u32_e32 v241, s58, v170
	v_add3_u32 v240, v240, v166, v160
	v_add3_u32 v242, v241, v165, v160
	ds_read_b64_tr_b16 v[240:241], v240
	ds_read_b64_tr_b16 v[242:243], v242
	s_waitcnt lgkmcnt(4)
	v_mfma_f32_32x32x16_bf16 v[0:15], v[232:235], v[132:135], v[0:15]
	v_add_u32_e32 v232, s59, v170
	v_add_u32_e32 v233, s60, v170
	v_add3_u32 v232, v232, v166, v160
	v_add3_u32 v234, v233, v165, v160
	ds_read_b64_tr_b16 v[232:233], v232
	ds_read_b64_tr_b16 v[234:235], v234
	s_waitcnt lgkmcnt(4)
	v_mfma_f32_32x32x16_bf16 v[112:127], v[236:239], v[128:131], v[112:127]
	v_add_u32_e32 v236, s61, v170
	v_add_u32_e32 v237, s62, v170
	v_add3_u32 v236, v236, v166, v160
	v_add3_u32 v238, v237, v165, v160
	ds_read_b64_tr_b16 v[236:237], v236
	ds_read_b64_tr_b16 v[238:239], v238
	s_waitcnt lgkmcnt(4)
	v_mfma_f32_32x32x16_bf16 v[96:111], v[240:243], v[128:131], v[96:111]
	v_add_u32_e32 v240, s63, v170
	v_add_u32_e32 v241, s64, v170
	v_add3_u32 v240, v240, v166, v160
	v_add3_u32 v242, v241, v165, v160
	ds_read_b64_tr_b16 v[240:241], v240
	ds_read_b64_tr_b16 v[242:243], v242
	s_waitcnt lgkmcnt(4)
	v_mfma_f32_32x32x16_bf16 v[80:95], v[232:235], v[128:131], v[80:95]
	v_add_u32_e32 v232, s65, v170
	v_add_u32_e32 v233, s6, v170
	v_add3_u32 v232, v232, v166, v160
	v_add3_u32 v234, v233, v165, v160
	ds_read_b64_tr_b16 v[232:233], v232
	ds_read_b64_tr_b16 v[234:235], v234
	s_waitcnt lgkmcnt(4)
	v_mfma_f32_32x32x16_bf16 v[64:79], v[236:239], v[128:131], v[64:79]
	v_add_u32_e32 v236, s7, v170
	v_add_u32_e32 v237, s66, v170
	v_add3_u32 v236, v236, v166, v160
	v_add3_u32 v238, v237, v165, v160
	ds_read_b64_tr_b16 v[236:237], v236
	ds_read_b64_tr_b16 v[238:239], v238
	s_waitcnt lgkmcnt(4)
; DI unsigned pk2(float lo, float hi) { bf2_t v = __builtin_convertvector((f32x2){lo, hi}, bf2_t); return __builtin_bit_cast(unsigned, v); }
; #define MFMA32(a, b, c) __builtin_amdgcn_mfma_f32_32x32x16_bf16((a), (b), (c), 0, 0, 0)
; DI void xattn_unit(const bf16_t* __restrict__ Qg, const bf16_t* __restrict__ Kg, const bf16_t* __restrict__ Vg, bf16_t* __restrict__ Og, lds_t* shm) {
;     ...
;   const float l = rs + __shfl_xor(rs, 32);
;     ...
;         O[c] = MFMA32(vf, P[t][ks >> 1][ks & 1], O[c]);
;       }
;   }
;   const float inv = 1.0f / l;
;   const unsigned ooff = ((unsigned)l31 * (unsigned)LDQ + 4u * h) * 2u;
; #pragma unroll
;   for (int c = 0; c < NC; ++c)
; #pragma unroll
;     for (int g4 = 0; g4 < 4; ++g4) {
;       u32x2 w; w.x = pk2(O[c][4 * g4 + 0] * inv, O[c][4 * g4 + 1] * inv); w.y = pk2(O[c][4 * g4 + 2] * inv, O[c][4 * g4 + 3] * inv);
;       gst<u32x2>(Og + 32 * c + 8 * g4, ooff, w);
	v_mfma_f32_32x32x16_bf16 v[48:63], v[240:243], v[128:131], v[48:63]
	v_add_u32_e32 v240, s16, v170
	v_add_u32_e32 v241, s17, v170
	v_add3_u32 v240, v240, v166, v160
	v_add3_u32 v242, v241, v165, v160
	ds_read_b64_tr_b16 v[240:241], v240
	ds_read_b64_tr_b16 v[242:243], v242
	s_waitcnt lgkmcnt(4)
	v_mfma_f32_32x32x16_bf16 v[32:47], v[232:235], v[128:131], v[32:47]
	s_waitcnt lgkmcnt(2)
	v_mfma_f32_32x32x16_bf16 v[16:31], v[236:239], v[128:131], v[16:31]
	s_waitcnt lgkmcnt(0)
	v_mfma_f32_32x32x16_bf16 v[0:15], v[240:243], v[128:131], v[0:15]
	v_add_f32_e32 v128, v167, v168
	v_div_scale_f32 v129, s[0:1], v128, v128, 1.0
	v_rcp_f32_e32 v130, v129
	v_readlane_b32 s0, v254, 6
	s_mov_b32 s28, s0
	s_mul_i32 s0, s2, s0
	v_fma_f32 v131, -v129, v130, 1.0
	v_fmac_f32_e32 v130, v131, v130
	v_div_scale_f32 v131, vcc, 1.0, v128, 1.0
	v_mul_f32_e32 v132, v131, v130
	v_fma_f32 v133, -v129, v132, v131
	v_fmac_f32_e32 v132, v133, v130
	v_fma_f32 v129, -v129, v132, v131
	v_div_fmas_f32 v129, v129, v130, v132
	v_div_fixup_f32 v128, v129, v128, 1.0
	v_lshl_or_b32 v129, v163, 3, v164
	v_mbcnt_lo_u32_b32 v130, -1, 0
	v_mbcnt_hi_u32_b32 v130, -1, v130
	v_and_b32_e32 v130, 32, v130
	v_lshrrev_b32_e32 v130, 2, v130
	v_add_u32_e32 v129, v129, v130
	v_pk_mul_f32 v[112:113], v[128:129], v[112:113] op_sel_hi:[0,1]
	v_pk_mul_f32 v[114:115], v[128:129], v[114:115] op_sel_hi:[0,1]
	v_pk_mul_f32 v[116:117], v[128:129], v[116:117] op_sel_hi:[0,1]
	v_pk_mul_f32 v[118:119], v[128:129], v[118:119] op_sel_hi:[0,1]
	v_pk_mul_f32 v[120:121], v[128:129], v[120:121] op_sel_hi:[0,1]
	v_pk_mul_f32 v[122:123], v[128:129], v[122:123] op_sel_hi:[0,1]
	v_pk_mul_f32 v[124:125], v[128:129], v[124:125] op_sel_hi:[0,1]
	v_pk_mul_f32 v[126:127], v[128:129], v[126:127] op_sel_hi:[0,1]
	v_pk_mul_f32 v[96:97], v[128:129], v[96:97] op_sel_hi:[0,1]
	v_pk_mul_f32 v[98:99], v[128:129], v[98:99] op_sel_hi:[0,1]
	v_pk_mul_f32 v[100:101], v[128:129], v[100:101] op_sel_hi:[0,1]
	v_pk_mul_f32 v[102:103], v[128:129], v[102:103] op_sel_hi:[0,1]
	v_pk_mul_f32 v[104:105], v[128:129], v[104:105] op_sel_hi:[0,1]
	v_pk_mul_f32 v[106:107], v[128:129], v[106:107] op_sel_hi:[0,1]
	v_pk_mul_f32 v[108:109], v[128:129], v[108:109] op_sel_hi:[0,1]
	v_pk_mul_f32 v[110:111], v[128:129], v[110:111] op_sel_hi:[0,1]
	v_pk_mul_f32 v[80:81], v[128:129], v[80:81] op_sel_hi:[0,1]
	v_pk_mul_f32 v[82:83], v[128:129], v[82:83] op_sel_hi:[0,1]
	v_pk_mul_f32 v[84:85], v[128:129], v[84:85] op_sel_hi:[0,1]
	v_pk_mul_f32 v[86:87], v[128:129], v[86:87] op_sel_hi:[0,1]
	v_pk_mul_f32 v[88:89], v[128:129], v[88:89] op_sel_hi:[0,1]
	v_pk_mul_f32 v[90:91], v[128:129], v[90:91] op_sel_hi:[0,1]
	v_pk_mul_f32 v[92:93], v[128:129], v[92:93] op_sel_hi:[0,1]
	v_pk_mul_f32 v[94:95], v[128:129], v[94:95] op_sel_hi:[0,1]
	v_pk_mul_f32 v[64:65], v[128:129], v[64:65] op_sel_hi:[0,1]
	v_pk_mul_f32 v[66:67], v[128:129], v[66:67] op_sel_hi:[0,1]
	v_pk_mul_f32 v[68:69], v[128:129], v[68:69] op_sel_hi:[0,1]
	v_pk_mul_f32 v[70:71], v[128:129], v[70:71] op_sel_hi:[0,1]
	v_pk_mul_f32 v[72:73], v[128:129], v[72:73] op_sel_hi:[0,1]
	v_pk_mul_f32 v[74:75], v[128:129], v[74:75] op_sel_hi:[0,1]
	v_pk_mul_f32 v[76:77], v[128:129], v[76:77] op_sel_hi:[0,1]
	v_pk_mul_f32 v[78:79], v[128:129], v[78:79] op_sel_hi:[0,1]
	v_pk_mul_f32 v[48:49], v[128:129], v[48:49] op_sel_hi:[0,1]
	v_pk_mul_f32 v[50:51], v[128:129], v[50:51] op_sel_hi:[0,1]
	v_pk_mul_f32 v[52:53], v[128:129], v[52:53] op_sel_hi:[0,1]
	v_pk_mul_f32 v[54:55], v[128:129], v[54:55] op_sel_hi:[0,1]
	v_pk_mul_f32 v[56:57], v[128:129], v[56:57] op_sel_hi:[0,1]
	v_pk_mul_f32 v[58:59], v[128:129], v[58:59] op_sel_hi:[0,1]
	v_pk_mul_f32 v[60:61], v[128:129], v[60:61] op_sel_hi:[0,1]
	v_pk_mul_f32 v[62:63], v[128:129], v[62:63] op_sel_hi:[0,1]
	v_pk_mul_f32 v[32:33], v[128:129], v[32:33] op_sel_hi:[0,1]
	v_pk_mul_f32 v[34:35], v[128:129], v[34:35] op_sel_hi:[0,1]
	v_pk_mul_f32 v[36:37], v[128:129], v[36:37] op_sel_hi:[0,1]
	v_pk_mul_f32 v[38:39], v[128:129], v[38:39] op_sel_hi:[0,1]
	v_pk_mul_f32 v[40:41], v[128:129], v[40:41] op_sel_hi:[0,1]
	v_pk_mul_f32 v[42:43], v[128:129], v[42:43] op_sel_hi:[0,1]
	v_pk_mul_f32 v[44:45], v[128:129], v[44:45] op_sel_hi:[0,1]
	v_pk_mul_f32 v[46:47], v[128:129], v[46:47] op_sel_hi:[0,1]
	v_pk_mul_f32 v[16:17], v[128:129], v[16:17] op_sel_hi:[0,1]
	v_pk_mul_f32 v[18:19], v[128:129], v[18:19] op_sel_hi:[0,1]
	v_pk_mul_f32 v[20:21], v[128:129], v[20:21] op_sel_hi:[0,1]
	v_pk_mul_f32 v[22:23], v[128:129], v[22:23] op_sel_hi:[0,1]
	v_pk_mul_f32 v[24:25], v[128:129], v[24:25] op_sel_hi:[0,1]
	v_pk_mul_f32 v[26:27], v[128:129], v[26:27] op_sel_hi:[0,1]
	v_pk_mul_f32 v[28:29], v[128:129], v[28:29] op_sel_hi:[0,1]
	v_pk_mul_f32 v[30:31], v[128:129], v[30:31] op_sel_hi:[0,1]
	v_pk_mul_f32 v[0:1], v[128:129], v[0:1] op_sel_hi:[0,1]
	v_pk_mul_f32 v[2:3], v[128:129], v[2:3] op_sel_hi:[0,1]
	v_pk_mul_f32 v[4:5], v[128:129], v[4:5] op_sel_hi:[0,1]
	v_pk_mul_f32 v[6:7], v[128:129], v[6:7] op_sel_hi:[0,1]
	v_pk_mul_f32 v[8:9], v[128:129], v[8:9] op_sel_hi:[0,1]
	v_pk_mul_f32 v[10:11], v[128:129], v[10:11] op_sel_hi:[0,1]
	v_pk_mul_f32 v[12:13], v[128:129], v[12:13] op_sel_hi:[0,1]
	v_pk_mul_f32 v[14:15], v[128:129], v[14:15] op_sel_hi:[0,1]
	s_nop 1
	v_permlane32_swap_b32_e32 v112, v116
	v_permlane32_swap_b32_e32 v113, v117
	v_permlane32_swap_b32_e32 v114, v118
	v_permlane32_swap_b32_e32 v115, v119
; DI unsigned pk2(float lo, float hi) { bf2_t v = __builtin_convertvector((f32x2){lo, hi}, bf2_t); return __builtin_bit_cast(unsigned, v); }
; DI void xattn_unit(const bf16_t* __restrict__ Qg, const bf16_t* __restrict__ Kg, const bf16_t* __restrict__ Vg, bf16_t* __restrict__ Og, lds_t* shm) {
;     ...
;   const float inv = 1.0f / l;
;   const unsigned ooff = ((unsigned)l31 * (unsigned)LDQ + 4u * h) * 2u;
; #pragma unroll
;   for (int c = 0; c < NC; ++c)
; #pragma unroll
;     for (int g4 = 0; g4 < 4; ++g4) {
;       u32x2 w; w.x = pk2(O[c][4 * g4 + 0] * inv, O[c][4 * g4 + 1] * inv); w.y = pk2(O[c][4 * g4 + 2] * inv, O[c][4 * g4 + 3] * inv);
;       gst<u32x2>(Og + 32 * c + 8 * g4, ooff, w);
;     }
	v_permlane32_swap_b32_e32 v120, v124
	v_permlane32_swap_b32_e32 v121, v125
	v_permlane32_swap_b32_e32 v122, v126
	v_permlane32_swap_b32_e32 v123, v127
	v_permlane32_swap_b32_e32 v96, v100
	v_permlane32_swap_b32_e32 v97, v101
	v_permlane32_swap_b32_e32 v98, v102
	v_permlane32_swap_b32_e32 v99, v103
	v_permlane32_swap_b32_e32 v104, v108
	v_permlane32_swap_b32_e32 v105, v109
	v_permlane32_swap_b32_e32 v106, v110
	v_permlane32_swap_b32_e32 v107, v111
	v_permlane32_swap_b32_e32 v80, v84
	v_permlane32_swap_b32_e32 v81, v85
	v_permlane32_swap_b32_e32 v82, v86
	v_permlane32_swap_b32_e32 v83, v87
	v_permlane32_swap_b32_e32 v88, v92
	v_permlane32_swap_b32_e32 v89, v93
	v_permlane32_swap_b32_e32 v90, v94
	v_permlane32_swap_b32_e32 v91, v95
	v_permlane32_swap_b32_e32 v64, v68
	v_permlane32_swap_b32_e32 v65, v69
	v_permlane32_swap_b32_e32 v66, v70
	v_permlane32_swap_b32_e32 v67, v71
	v_permlane32_swap_b32_e32 v72, v76
	v_permlane32_swap_b32_e32 v73, v77
	v_permlane32_swap_b32_e32 v74, v78
	v_permlane32_swap_b32_e32 v75, v79
	v_permlane32_swap_b32_e32 v48, v52
	v_permlane32_swap_b32_e32 v49, v53
	v_permlane32_swap_b32_e32 v50, v54
	v_permlane32_swap_b32_e32 v51, v55
	v_permlane32_swap_b32_e32 v56, v60
	v_permlane32_swap_b32_e32 v57, v61
	v_permlane32_swap_b32_e32 v58, v62
	v_permlane32_swap_b32_e32 v59, v63
	v_permlane32_swap_b32_e32 v32, v36
	v_permlane32_swap_b32_e32 v33, v37
	v_permlane32_swap_b32_e32 v34, v38
	v_permlane32_swap_b32_e32 v35, v39
	v_permlane32_swap_b32_e32 v40, v44
	v_permlane32_swap_b32_e32 v41, v45
	v_permlane32_swap_b32_e32 v42, v46
	v_permlane32_swap_b32_e32 v43, v47
	v_permlane32_swap_b32_e32 v16, v20
	v_permlane32_swap_b32_e32 v17, v21
	v_permlane32_swap_b32_e32 v18, v22
	v_permlane32_swap_b32_e32 v19, v23
	v_permlane32_swap_b32_e32 v24, v28
	v_permlane32_swap_b32_e32 v25, v29
	v_permlane32_swap_b32_e32 v26, v30
	v_permlane32_swap_b32_e32 v27, v31
	v_permlane32_swap_b32_e32 v0, v4
	v_permlane32_swap_b32_e32 v1, v5
	v_permlane32_swap_b32_e32 v2, v6
	v_permlane32_swap_b32_e32 v3, v7
	v_permlane32_swap_b32_e32 v8, v12
	v_permlane32_swap_b32_e32 v9, v13
	v_permlane32_swap_b32_e32 v10, v14
	v_permlane32_swap_b32_e32 v11, v15
	v_cvt_pk_bf16_f32 v112, v112, v113
	v_cvt_pk_bf16_f32 v113, v114, v115
	v_cvt_pk_bf16_f32 v114, v116, v117
	v_cvt_pk_bf16_f32 v115, v118, v119
	global_store_dwordx4 v129, v[112:115], s[30:31]
	v_cvt_pk_bf16_f32 v120, v120, v121
	v_cvt_pk_bf16_f32 v121, v122, v123
	v_cvt_pk_bf16_f32 v122, v124, v125
	v_cvt_pk_bf16_f32 v123, v126, v127
	global_store_dwordx4 v129, v[120:123], s[30:31] offset:32
	v_cvt_pk_bf16_f32 v96, v96, v97
	v_cvt_pk_bf16_f32 v97, v98, v99
	v_cvt_pk_bf16_f32 v98, v100, v101
	v_cvt_pk_bf16_f32 v99, v102, v103
	global_store_dwordx4 v129, v[96:99], s[30:31] offset:64
	v_cvt_pk_bf16_f32 v104, v104, v105
	v_cvt_pk_bf16_f32 v105, v106, v107
	v_cvt_pk_bf16_f32 v106, v108, v109
	v_cvt_pk_bf16_f32 v107, v110, v111
	global_store_dwordx4 v129, v[104:107], s[30:31] offset:96
	v_cvt_pk_bf16_f32 v80, v80, v81
	v_cvt_pk_bf16_f32 v81, v82, v83
	v_cvt_pk_bf16_f32 v82, v84, v85
	v_cvt_pk_bf16_f32 v83, v86, v87
	global_store_dwordx4 v129, v[80:83], s[30:31] offset:128
	v_cvt_pk_bf16_f32 v88, v88, v89
	v_cvt_pk_bf16_f32 v89, v90, v91
	v_cvt_pk_bf16_f32 v90, v92, v93
	v_cvt_pk_bf16_f32 v91, v94, v95
	global_store_dwordx4 v129, v[88:91], s[30:31] offset:160
	v_cvt_pk_bf16_f32 v64, v64, v65
	v_cvt_pk_bf16_f32 v65, v66, v67
	v_cvt_pk_bf16_f32 v66, v68, v69
	v_cvt_pk_bf16_f32 v67, v70, v71
	global_store_dwordx4 v129, v[64:67], s[30:31] offset:192
	v_cvt_pk_bf16_f32 v72, v72, v73
	v_cvt_pk_bf16_f32 v73, v74, v75
	v_cvt_pk_bf16_f32 v74, v76, v77
	v_cvt_pk_bf16_f32 v75, v78, v79
	global_store_dwordx4 v129, v[72:75], s[30:31] offset:224
	v_cvt_pk_bf16_f32 v48, v48, v49
	v_cvt_pk_bf16_f32 v49, v50, v51
	v_cvt_pk_bf16_f32 v50, v52, v53
	v_cvt_pk_bf16_f32 v51, v54, v55
	global_store_dwordx4 v129, v[48:51], s[30:31] offset:256
	v_cvt_pk_bf16_f32 v56, v56, v57
	v_cvt_pk_bf16_f32 v57, v58, v59
	v_cvt_pk_bf16_f32 v58, v60, v61
	v_cvt_pk_bf16_f32 v59, v62, v63
	global_store_dwordx4 v129, v[56:59], s[30:31] offset:288
	v_cvt_pk_bf16_f32 v32, v32, v33
	v_cvt_pk_bf16_f32 v33, v34, v35
	v_cvt_pk_bf16_f32 v34, v36, v37
	v_cvt_pk_bf16_f32 v35, v38, v39
	global_store_dwordx4 v129, v[32:35], s[30:31] offset:320
	v_cvt_pk_bf16_f32 v40, v40, v41
	v_cvt_pk_bf16_f32 v41, v42, v43
	v_cvt_pk_bf16_f32 v42, v44, v45
	v_cvt_pk_bf16_f32 v43, v46, v47
	global_store_dwordx4 v129, v[40:43], s[30:31] offset:352
	v_cvt_pk_bf16_f32 v16, v16, v17
	v_cvt_pk_bf16_f32 v17, v18, v19
	v_cvt_pk_bf16_f32 v18, v20, v21
	v_cvt_pk_bf16_f32 v19, v22, v23
	global_store_dwordx4 v129, v[16:19], s[30:31] offset:384
	v_cvt_pk_bf16_f32 v24, v24, v25
	v_cvt_pk_bf16_f32 v25, v26, v27
	v_cvt_pk_bf16_f32 v26, v28, v29
	v_cvt_pk_bf16_f32 v27, v30, v31
	global_store_dwordx4 v129, v[24:27], s[30:31] offset:416
	v_cvt_pk_bf16_f32 v0, v0, v1
	v_cvt_pk_bf16_f32 v1, v2, v3
	v_cvt_pk_bf16_f32 v2, v4, v5
	v_cvt_pk_bf16_f32 v3, v6, v7
	global_store_dwordx4 v129, v[0:3], s[30:31] offset:448
	v_cvt_pk_bf16_f32 v8, v8, v9
	v_cvt_pk_bf16_f32 v9, v10, v11
	v_cvt_pk_bf16_f32 v10, v12, v13
	v_cvt_pk_bf16_f32 v11, v14, v15
	global_store_dwordx4 v129, v[8:11], s[30:31] offset:480
	s_add_i32 s0, s0, s68
	s_add_i32 s33, s33, s28
	s_cmpk_lt_i32 s33, 0x200
	v_readlane_b32 s1, v254, 7
	s_cbranch_scc0 .LBB0_634
